# gemm8 prologue: k-tile-1 LDS-DMA issued ahead of zeroing/fragment reads, conservative vmcnt(8) dropped; tile decode u32 division by 8*gn (power of two) replaced by ff1+shift; stacked on v59
# speedup vs baseline: 1.0045x; 1.0045x over previous
; DI void g8_decode(int u, int x, int nN, int& pm, int& pn) {
;   const int ng = u >> 6, rem = u & 63;
;   int gn = nN - 4 * ng; if (gn > 4) gn = 4;
;   const int mg = rem / (8 * gn), jj = rem % (8 * gn);
;   pm = 16 * x + 8 * mg + (jj & 7); pn = 4 * ng + (jj >> 3);
; }
; template <class Epi>
; DI void gemm8_phase(int x, int j, const bf16_t* __restrict__ A, int lda, const bf16_t* __restrict__ Bt, int K, int N, int a_grp, const Epi epi) {
;     ...
;   for (int u = j; u < total; u += nb) {
;     int pm, pn; g8_decode(u, x, nN, pm, pn);
;     const int brow = pm * 256, bcol = pn * 256;
;     const bf16_t* Ab = A + (size_t)brow * lda + (a_grp ? (bcol / a_grp) * K : 0);
;     const bf16_t* Bb = Bt + (size_t)bcol * ldb;
;     const bool has_next = (u + nb < total);
;     const bf16_t* Abn = Ab; const bf16_t* Bbn = Bb;
;     if (has_next) {
;       int pm2, pn2; g8_decode(u + nb, x, nN, pm2, pn2);
;       Abn = A + (size_t)(pm2 * 256) * lda + (a_grp ? ((pn2 * 256) / a_grp) * K : 0);
;       Bbn = Bt + (size_t)(pn2 * 256) * ldb;
;     }
.LBB0_457:
	s_ashr_i32 s0, s2, 4
	s_and_b32 s0, s0, -4
	s_sub_i32 s1, 22, s0
	s_min_i32 s1, s1, 4
	s_lshl_b32 s3, s1, 3
	s_abs_i32 s6, s3
	s_ashr_i32 s58, s1, 31
	s_and_b32 s7, s2, 63
	s_ff1_i32_b32 s10, s6
	s_lshr_b32 s1, s7, s10
	s_xor_b32 s59, s1, s58
	s_sub_i32 s1, s59, s58
	s_mul_i32 s3, s1, s3
	s_lshl_b32 s1, s1, 3
	s_sub_i32 s3, s7, s3
	s_add_i32 s1, s1, s28
	s_and_b32 s70, s3, 7
	s_lshr_b32 s3, s3, 3
	s_or_b32 s1, s1, s70
	s_add_i32 s6, s3, s0
	s_lshl_b32 s3, s1, 8
	s_lshl_b32 s31, s6, 8
	s_mul_i32 s1, s1, 0x88000
	s_mul_hi_i32 s7, s3, 0x880
	s_add_u32 s0, s50, s1
	s_addc_u32 s1, s51, s7
	s_mul_i32 s71, s6, 0x88000
	s_mul_hi_i32 s78, s31, 0x880
	s_add_u32 s14, s34, s71
	s_addc_u32 s15, s35, s78
	s_add_i32 s2, s2, s33
	s_cmpk_lt_i32 s2, 0x160
	s_cselect_b64 s[54:55], -1, 0
	s_cmpk_gt_i32 s2, 0x15f
	s_cselect_b64 s[6:7], -1, 0
	s_and_b64 vcc, exec, s[6:7]
	s_mov_b64 s[10:11], s[0:1]
	s_mov_b64 s[38:39], s[14:15]
	s_cbranch_vccnz .LBB0_459
	s_ashr_i32 s10, s2, 4
	s_and_b32 s10, s10, -4
	s_sub_i32 s11, 22, s10
	s_min_i32 s11, s11, 4
	s_lshl_b32 s38, s11, 3
	s_abs_i32 s39, s38
	s_and_b32 s79, s2, 63
	s_ashr_i32 s11, s11, 31
	s_ff1_i32_b32 s84, s39
	s_lshr_b32 s39, s79, s84
	s_xor_b32 s39, s39, s11
	s_sub_i32 s11, s39, s11
	s_mul_i32 s38, s11, s38
	s_lshl_b32 s11, s11, 3
	s_sub_i32 s38, s79, s38
	s_add_i32 s11, s11, s28
	s_and_b32 s39, s38, 7
	s_lshr_b32 s38, s38, 3
	s_or_b32 s11, s11, s39
	s_add_i32 s38, s38, s10
	s_lshl_b32 s10, s11, 8
	s_mul_i32 s11, s11, 0x88000
	s_mul_hi_i32 s39, s10, 0x880
	s_add_u32 s10, s50, s11
	s_addc_u32 s11, s51, s39
	s_lshl_b32 s39, s38, 8
	s_mul_i32 s38, s38, 0x88000
	s_mul_hi_i32 s39, s39, 0x880
	s_add_u32 s38, s34, s38
	s_movk_i32 s79, 0xffe0
	s_addc_u32 s39, s35, s39

; DI int opaque_tid512() { int t = threadIdx.x; asm volatile("" : "+v"(t)); return t; }
; #define G8_STAGE(buf_, ap_, bp_) G8_STAGE_R(buf_, ap_, bp_, 0, 4)
; template <class Epi>
; DI void gemm8_tile(const bf16_t* __restrict__ Ab, int lda, const bf16_t* __restrict__ Bb, int ldb, int K, int brow, int bcol, const Epi epi,
;                    bool staged, bool has_next, const bf16_t* __restrict__ Abn, const bf16_t* __restrict__ Bbn) {
;   const int tid = opaque_tid512(), wid = tid >> 6, lane = tid & 63, wr = wid >> 2, wc = wid & 3, fr = lane & 15, fq = lane >> 4;
;   unsigned aoff[4], boff[4];
; #pragma unroll
;   for (int i = 0; i < 4; ++i) { int R, C; stage_rc2(wid * 1024 + i * 8192 + lane * 16, R, C); aoff[i] = (unsigned)R * (unsigned)lda + (unsigned)C; boff[i] = (unsigned)R * (unsigned)ldb + (unsigned)C; }
;     ...
;   f32x4 acc[8][4];
; #pragma unroll
;   for (int m = 0; m < 8; ++m)
; #pragma unroll
;     for (int n = 0; n < 4; ++n) acc[m][n] = (f32x4){0.f, 0.f, 0.f, 0.f};
;   const int nt = K / 64;
;   if (!staged) {
;     G8_STAGE(0, Ab, Bb);
;     asm volatile("s_waitcnt vmcnt(0)" ::: "memory");
;     __syncthreads();
;   }
;   for (int t = 0; t < nt; ++t) {
;     const int cur = t & 1;
;     const unsigned char* sa = smem + cur * G8_STAGE_B;
;     const unsigned char* sb = sa + G8_TILE_B;
; #pragma unroll
;     for (int ks = 0; ks < 2; ++ks) {
;       bf16x8 At[8], Bf[4];
;       Bf[0] = *(const bf16x8*)(sb + lds_byte2(wc * 64 + fr, ks * 32 + fq * 8));
;       At[0] = *(const bf16x8*)(sa + lds_byte2(wr * 128 + fr, ks * 32 + fq * 8));
; #pragma unroll
;       for (int n = 1; n < 4; ++n) Bf[n] = *(const bf16x8*)(sb + lds_byte2(wc * 64 + n * 16 + fr, ks * 32 + fq * 8));
; #pragma unroll
;       for (int m = 1; m < 8; ++m) At[m] = *(const bf16x8*)(sa + lds_byte2(wr * 128 + m * 16 + fr, ks * 32 + fq * 8));
;       {
;         __builtin_amdgcn_sched_barrier(0);
;         if (t + 1 < nt) { G8_STAGE_R(cur ^ 1, Ab + (t + 1) * 64, Bb + (t + 1) * 64, 2 * ks, 2 * ks + 2); }
;         else if (has_next) { G8_STAGE_R(0, Abn, Bbn, 2 * ks, 2 * ks + 2); }
.LBB0_461:
	v_readlane_b32 s0, v253, 4
	s_add_u32 s0, s0, s71
	v_readlane_b32 s1, v253, 5
	v_lshlrev_b64 v[212:213], 1, v[0:1]
	s_addc_u32 s1, s1, s78
	v_lshlrev_b64 v[214:215], 1, v[6:7]
	v_lshlrev_b64 v[146:147], 1, v[4:5]
	v_lshlrev_b64 v[148:149], 1, v[2:3]
	v_lshl_add_u64 v[130:131], s[0:1], 0, v[212:213]
	v_lshl_add_u64 v[132:133], s[0:1], 0, v[214:215]
	v_lshl_add_u64 v[134:135], s[0:1], 0, v[146:147]
	v_lshl_add_u64 v[136:137], s[0:1], 0, v[148:149]
	s_lshl_b32 s0, s59, 3
	s_add_i32 s0, s28, s0
	s_add_i32 s0, s0, s70
	s_lshl_b32 s1, s58, 3
	s_sub_i32 s0, s0, s1
	s_lshl_b32 s1, s0, 8
	s_mul_i32 s0, s0, 0x88000
	v_readlane_b32 s8, v253, 6
	v_and_b32_e32 v228, 63, v8
	v_and_b32_e32 v229, 3, v9
	v_ashrrev_i32_e32 v9, 8, v8
	v_and_b32_e32 v223, 15, v8
	v_and_b32_e32 v10, 48, v8
	v_lshlrev_b32_e32 v12, 2, v8
	v_lshlrev_b32_e32 v8, 6, v8
	s_mul_hi_i32 s1, s1, 0x880
	s_add_u32 s0, s8, s0
	v_readlane_b32 s8, v253, 7
	v_lshlrev_b32_e32 v11, 6, v223
	v_and_b32_e32 v12, 32, v12
	v_lshlrev_b32_e32 v153, 14, v9
	v_and_b32_e32 v8, 0x3c0, v8
	s_addc_u32 s1, s8, s1
	v_mov_b32_e32 v2, 0
	v_lshlrev_b32_e32 v151, 13, v229
	v_bitop3_b32 v152, v11, v12, v10 bitop3:0x36
	v_lshlrev_b32_e32 v230, 7, v9
	v_or_b32_e32 v150, 0x800, v153
	v_bitop3_b32 v158, v8, v12, v10 bitop3:0x36
	v_or_b32_e32 v167, 0x1000, v153
	v_or_b32_e32 v166, 0x1800, v153
	v_or_b32_e32 v165, 0x2000, v153
	v_or_b32_e32 v164, 0x2800, v153
	v_or_b32_e32 v163, 0x3000, v153
	v_or_b32_e32 v162, 0x3800, v153
	v_lshl_add_u64 v[138:139], s[0:1], 0, v[212:213]
	v_lshl_add_u64 v[140:141], s[0:1], 0, v[214:215]
	v_lshl_add_u64 v[142:143], s[0:1], 0, v[146:147]
	v_lshl_add_u64 v[144:145], s[0:1], 0, v[148:149]
	s_mov_b64 s[0:1], 0
	s_mov_b32 s14, 0
	v_add_u32_e32 v244, 0x10000, v157
	s_nop 0
	v_readfirstlane_b32 s56, v244
	s_mov_b32 m0, s56
	v_lshl_add_u64 v[160:161], v[144:145], 0, s[0:1]
	global_load_lds_dwordx4 v[160:161], off
	s_add_u32 m0, s56, 0x8000
	v_lshl_add_u64 v[160:161], v[136:137], 0, s[0:1]
	global_load_lds_dwordx4 v[160:161], off
	s_add_u32 m0, s56, 0x2000
	v_lshl_add_u64 v[160:161], v[142:143], 0, s[0:1]
	global_load_lds_dwordx4 v[160:161], off
	s_add_u32 m0, s56, 0xa000
	v_lshl_add_u64 v[160:161], v[134:135], 0, s[0:1]
	global_load_lds_dwordx4 v[160:161], off
	s_add_u32 m0, s56, 0x4000
	v_lshl_add_u64 v[160:161], v[140:141], 0, s[0:1]
	global_load_lds_dwordx4 v[160:161], off
	s_add_u32 m0, s56, 0xc000
	v_lshl_add_u64 v[160:161], v[132:133], 0, s[0:1]
	global_load_lds_dwordx4 v[160:161], off
	s_add_u32 m0, s56, 0x6000
	v_lshl_add_u64 v[160:161], v[138:139], 0, s[0:1]
	global_load_lds_dwordx4 v[160:161], off
	s_add_u32 m0, s56, 0xe000
	v_lshl_add_u64 v[160:161], v[130:131], 0, s[0:1]
	global_load_lds_dwordx4 v[160:161], off
	v_mov_b32_e32 v3, v2
	v_mov_b32_e32 v4, v2
	v_mov_b32_e32 v5, v2
	v_mov_b32_e32 v6, v2
	v_mov_b32_e32 v7, v2
	v_mov_b32_e32 v8, v2
	v_mov_b32_e32 v9, v2
	v_mov_b32_e32 v10, v2
	v_mov_b32_e32 v11, v2
	v_mov_b32_e32 v12, v2
	v_mov_b32_e32 v13, v2
	v_mov_b32_e32 v14, v2
	v_mov_b32_e32 v15, v2
	v_mov_b32_e32 v16, v2
	v_mov_b32_e32 v17, v2
	v_mov_b32_e32 v18, v2
	v_mov_b32_e32 v19, v2
	v_mov_b32_e32 v20, v2
	v_mov_b32_e32 v21, v2
	v_mov_b32_e32 v22, v2
	v_mov_b32_e32 v23, v2
	v_mov_b32_e32 v24, v2
	v_mov_b32_e32 v25, v2
	v_mov_b32_e32 v26, v2
	v_mov_b32_e32 v27, v2
	v_mov_b32_e32 v28, v2
	v_mov_b32_e32 v29, v2
	v_mov_b32_e32 v30, v2
	v_mov_b32_e32 v31, v2
	v_mov_b32_e32 v32, v2
	v_mov_b32_e32 v33, v2
	v_mov_b32_e32 v34, v2
	v_mov_b32_e32 v35, v2
	v_mov_b32_e32 v36, v2
	v_mov_b32_e32 v37, v2
	v_mov_b32_e32 v38, v2
	v_mov_b32_e32 v39, v2
	v_mov_b32_e32 v40, v2
	v_mov_b32_e32 v41, v2
	v_mov_b32_e32 v42, v2
	v_mov_b32_e32 v43, v2
	v_mov_b32_e32 v44, v2
	v_mov_b32_e32 v45, v2
	v_mov_b32_e32 v46, v2
	v_mov_b32_e32 v47, v2
	v_mov_b32_e32 v48, v2
	v_mov_b32_e32 v49, v2
	v_mov_b32_e32 v50, v2
	v_mov_b32_e32 v51, v2
	v_mov_b32_e32 v52, v2
	v_mov_b32_e32 v53, v2
	v_mov_b32_e32 v54, v2
	v_mov_b32_e32 v55, v2
	v_mov_b32_e32 v56, v2
	v_mov_b32_e32 v57, v2
	v_mov_b32_e32 v58, v2
	v_mov_b32_e32 v59, v2
	v_mov_b32_e32 v60, v2
	v_mov_b32_e32 v61, v2
	v_mov_b32_e32 v62, v2
	v_mov_b32_e32 v63, v2
	v_mov_b32_e32 v64, v2
	v_mov_b32_e32 v65, v2
	v_mov_b32_e32 v66, v2
	v_mov_b32_e32 v67, v2
	v_mov_b32_e32 v68, v2
	v_mov_b32_e32 v69, v2
	v_mov_b32_e32 v70, v2
	v_mov_b32_e32 v71, v2
	v_mov_b32_e32 v72, v2
	v_mov_b32_e32 v73, v2
	v_mov_b32_e32 v74, v2
	v_mov_b32_e32 v75, v2
	v_mov_b32_e32 v76, v2
	v_mov_b32_e32 v77, v2
	v_mov_b32_e32 v78, v2
	v_mov_b32_e32 v79, v2
	v_mov_b32_e32 v80, v2
	v_mov_b32_e32 v81, v2
	v_mov_b32_e32 v82, v2
	v_mov_b32_e32 v83, v2
	v_mov_b32_e32 v84, v2
	v_mov_b32_e32 v85, v2
	v_mov_b32_e32 v86, v2
	v_mov_b32_e32 v87, v2
	v_mov_b32_e32 v88, v2
	v_mov_b32_e32 v89, v2
	v_mov_b32_e32 v90, v2
	v_mov_b32_e32 v91, v2
	v_mov_b32_e32 v92, v2
	v_mov_b32_e32 v93, v2
	v_mov_b32_e32 v94, v2
	v_mov_b32_e32 v95, v2
	v_mov_b32_e32 v96, v2
	v_mov_b32_e32 v97, v2
	v_mov_b32_e32 v98, v2
	v_mov_b32_e32 v99, v2
	v_mov_b32_e32 v100, v2
	v_mov_b32_e32 v101, v2
	v_mov_b32_e32 v102, v2
	v_mov_b32_e32 v103, v2
	v_mov_b32_e32 v104, v2
	v_mov_b32_e32 v105, v2
	v_mov_b32_e32 v106, v2
	v_mov_b32_e32 v107, v2
	v_mov_b32_e32 v108, v2
	v_mov_b32_e32 v109, v2
	v_mov_b32_e32 v110, v2
	v_mov_b32_e32 v111, v2
	v_mov_b32_e32 v112, v2
	v_mov_b32_e32 v113, v2
	v_mov_b32_e32 v114, v2
	v_mov_b32_e32 v115, v2
	v_mov_b32_e32 v116, v2
	v_mov_b32_e32 v117, v2
	v_mov_b32_e32 v118, v2
	v_mov_b32_e32 v119, v2
	v_mov_b32_e32 v120, v2
	v_mov_b32_e32 v121, v2
	v_mov_b32_e32 v122, v2
	v_mov_b32_e32 v123, v2
	v_mov_b32_e32 v124, v2
	v_mov_b32_e32 v125, v2
	v_mov_b32_e32 v126, v2
	v_mov_b32_e32 v127, v2
	v_mov_b32_e32 v128, v2
	v_mov_b32_e32 v129, v2
	s_mov_b32 s56, 0
	v_add3_u32 v0, s56, v152, v151
	v_add3_u32 v159, s56, v152, v153
	v_add3_u32 v209, s56, v158, v167
	v_add3_u32 v240, s56, v158, v165
	v_add3_u32 v242, s56, v158, v163
	v_add3_u32 v208, s56, v158, v150
	v_add3_u32 v231, s56, v158, v166
	v_add3_u32 v241, s56, v158, v164
	v_add3_u32 v243, s56, v158, v162
	ds_read_b128 v[168:171], v0 offset:32768
	ds_read_b128 v[172:175], v0 offset:34816
	ds_read_b128 v[184:187], v159
	ds_read_b128 v[188:191], v208
	ds_read_b128 v[192:195], v209
	ds_read_b128 v[196:199], v231
	ds_read_b128 v[200:203], v240
	ds_read_b128 v[204:207], v241
	ds_read_b128 v[232:235], v242
	ds_read_b128 v[236:239], v243
	ds_read_b128 v[176:179], v0 offset:36864
	ds_read_b128 v[180:183], v0 offset:38912

; DI void g8_decode(int u, int x, int nN, int& pm, int& pn) {
;   const int ng = u >> 6, rem = u & 63;
;   int gn = nN - 4 * ng; if (gn > 4) gn = 4;
;   const int mg = rem / (8 * gn), jj = rem % (8 * gn);
;   pm = 16 * x + 8 * mg + (jj & 7); pn = 4 * ng + (jj >> 3);
; }
; template <class Epi>
; DI void gemm8_phase(int x, int j, const bf16_t* __restrict__ A, int lda, const bf16_t* __restrict__ Bt, int K, int N, int a_grp, const Epi epi) {
;     ...
;   for (int u = j; u < total; u += nb) {
;     int pm, pn; g8_decode(u, x, nN, pm, pn);
;     const int brow = pm * 256, bcol = pn * 256;
;     const bf16_t* Ab = A + (size_t)brow * lda + (a_grp ? (bcol / a_grp) * K : 0);
;     const bf16_t* Bb = Bt + (size_t)bcol * ldb;
;     const bool has_next = (u + nb < total);
;     const bf16_t* Abn = Ab; const bf16_t* Bbn = Bb;
;     if (has_next) {
;       int pm2, pn2; g8_decode(u + nb, x, nN, pm2, pn2);
;       Abn = A + (size_t)(pm2 * 256) * lda + (a_grp ? ((pn2 * 256) / a_grp) * K : 0);
;       Bbn = Bt + (size_t)(pn2 * 256) * ldb;
;     }
.LBB0_478:
	s_ashr_i32 s8, s2, 4
	s_and_b32 s8, s8, -4
	s_sub_i32 s9, 4, s8
	s_min_i32 s9, s9, 4
	s_lshl_b32 s10, s9, 3
	s_ashr_i32 s70, s9, 31
	s_abs_i32 s9, s10
	s_and_b32 s3, s2, 63
	s_ff1_i32_b32 s14, s9
	s_lshr_b32 s9, s3, s14
	s_xor_b32 s71, s9, s70
	s_sub_i32 s9, s71, s70
	s_mul_i32 s10, s9, s10
	s_sub_i32 s3, s3, s10
	s_lshl_b32 s9, s9, 3
	s_add_i32 s9, s9, s28
	s_and_b32 s75, s3, 7
	s_lshr_b32 s3, s3, 3
	s_or_b32 s9, s9, s75
	s_add_i32 s8, s3, s8
	s_lshl_b32 s3, s9, 8
	s_lshl_b32 s31, s8, 8
	s_mul_i32 s9, s9, 0x168000
	s_mul_hi_i32 s10, s3, 0x1680
	s_add_u32 s56, s52, s9
	s_addc_u32 s57, s53, s10
	s_mul_i32 s78, s8, 0x168000
	s_mul_hi_i32 s79, s31, 0x1680
	s_add_u32 s58, s18, s78
	s_addc_u32 s59, s19, s79
	s_add_i32 s2, s2, s33
	s_cmp_lt_i32 s2, 64
	s_cselect_b64 s[14:15], -1, 0
	s_cmp_gt_i32 s2, 63
	s_cselect_b64 s[54:55], -1, 0
	s_and_b64 vcc, exec, s[54:55]
	s_mov_b64 s[8:9], s[56:57]
	s_mov_b64 s[10:11], s[58:59]
	s_cbranch_vccnz .LBB0_480
	s_ashr_i32 s8, s2, 4
	s_and_b32 s8, s8, -4
	s_sub_i32 s9, 4, s8
	s_min_i32 s9, s9, 4
	s_lshl_b32 s10, s9, 3
	s_abs_i32 s11, s10
	s_and_b32 s81, s2, 63
	s_ashr_i32 s9, s9, 31
	s_ff1_i32_b32 s85, s11
	s_lshr_b32 s11, s81, s85
	s_xor_b32 s11, s11, s9
	s_sub_i32 s9, s11, s9
	s_mul_i32 s10, s9, s10
	s_lshl_b32 s9, s9, 3
	s_sub_i32 s10, s81, s10
	s_add_i32 s9, s9, s28
	s_and_b32 s11, s10, 7
	s_lshr_b32 s10, s10, 3
	s_or_b32 s9, s9, s11
	s_add_i32 s10, s10, s8
	s_lshl_b32 s8, s9, 8
	s_mul_i32 s9, s9, 0x168000
	s_mul_hi_i32 s11, s8, 0x1680
	s_add_u32 s8, s52, s9
	s_addc_u32 s9, s53, s11
	s_lshl_b32 s11, s10, 8
	s_mul_i32 s10, s10, 0x168000
	s_mul_hi_i32 s11, s11, 0x1680
	s_add_u32 s10, s18, s10
	s_addc_u32 s11, s19, s11

; DI int opaque_tid512() { int t = threadIdx.x; asm volatile("" : "+v"(t)); return t; }
; #define G8_STAGE(buf_, ap_, bp_) G8_STAGE_R(buf_, ap_, bp_, 0, 4)
; template <class Epi>
; DI void gemm8_tile(const bf16_t* __restrict__ Ab, int lda, const bf16_t* __restrict__ Bb, int ldb, int K, int brow, int bcol, const Epi epi,
;                    bool staged, bool has_next, const bf16_t* __restrict__ Abn, const bf16_t* __restrict__ Bbn) {
;   const int tid = opaque_tid512(), wid = tid >> 6, lane = tid & 63, wr = wid >> 2, wc = wid & 3, fr = lane & 15, fq = lane >> 4;
;   unsigned aoff[4], boff[4];
; #pragma unroll
;   for (int i = 0; i < 4; ++i) { int R, C; stage_rc2(wid * 1024 + i * 8192 + lane * 16, R, C); aoff[i] = (unsigned)R * (unsigned)lda + (unsigned)C; boff[i] = (unsigned)R * (unsigned)ldb + (unsigned)C; }
;     ...
;   f32x4 acc[8][4];
; #pragma unroll
;   for (int m = 0; m < 8; ++m)
; #pragma unroll
;     for (int n = 0; n < 4; ++n) acc[m][n] = (f32x4){0.f, 0.f, 0.f, 0.f};
;   const int nt = K / 64;
;   if (!staged) {
;     G8_STAGE(0, Ab, Bb);
;     asm volatile("s_waitcnt vmcnt(0)" ::: "memory");
;     __syncthreads();
;   }
;   for (int t = 0; t < nt; ++t) {
;     const int cur = t & 1;
;     const unsigned char* sa = smem + cur * G8_STAGE_B;
;     const unsigned char* sb = sa + G8_TILE_B;
; #pragma unroll
;     for (int ks = 0; ks < 2; ++ks) {
;       bf16x8 At[8], Bf[4];
;       Bf[0] = *(const bf16x8*)(sb + lds_byte2(wc * 64 + fr, ks * 32 + fq * 8));
;       At[0] = *(const bf16x8*)(sa + lds_byte2(wr * 128 + fr, ks * 32 + fq * 8));
; #pragma unroll
;       for (int n = 1; n < 4; ++n) Bf[n] = *(const bf16x8*)(sb + lds_byte2(wc * 64 + n * 16 + fr, ks * 32 + fq * 8));
; #pragma unroll
;       for (int m = 1; m < 8; ++m) At[m] = *(const bf16x8*)(sa + lds_byte2(wr * 128 + m * 16 + fr, ks * 32 + fq * 8));
;       {
;         __builtin_amdgcn_sched_barrier(0);
;         if (t + 1 < nt) { G8_STAGE_R(cur ^ 1, Ab + (t + 1) * 64, Bb + (t + 1) * 64, 2 * ks, 2 * ks + 2); }
;         else if (has_next) { G8_STAGE_R(0, Abn, Bbn, 2 * ks, 2 * ks + 2); }
.LBB0_482:
	s_lshl_b32 s0, s71, 3
	s_add_i32 s0, s28, s0
	s_add_i32 s0, s0, s75
	s_lshl_b32 s1, s70, 3
	s_sub_i32 s0, s0, s1
	s_lshl_b32 s1, s0, 8
	s_mul_i32 s0, s0, 0x168000
	s_mul_hi_i32 s1, s1, 0x1680
	s_add_u32 s0, s91, s0
	v_lshlrev_b64 v[178:179], 1, v[4:5]
	s_addc_u32 s1, s72, s1
	v_lshlrev_b64 v[180:181], 1, v[2:3]
	v_lshlrev_b64 v[194:195], 1, v[6:7]
	v_lshlrev_b64 v[196:197], 1, v[0:1]
	v_and_b32_e32 v198, 15, v8
	v_lshl_add_u64 v[130:131], s[0:1], 0, v[178:179]
	v_lshl_add_u64 v[132:133], s[0:1], 0, v[180:181]
	v_lshl_add_u64 v[134:135], s[0:1], 0, v[194:195]
	v_lshl_add_u64 v[136:137], s[0:1], 0, v[196:197]
	v_readlane_b32 s0, v253, 8
	v_and_b32_e32 v206, 63, v8
	v_ashrrev_i32_e32 v10, 8, v8
	v_and_b32_e32 v204, 3, v9
	v_and_b32_e32 v9, 48, v8
	v_lshlrev_b32_e32 v199, 2, v198
	v_lshlrev_b32_e32 v8, 6, v8
	s_add_u32 s0, s0, s78
	v_readlane_b32 s1, v253, 9
	v_lshlrev_b32_e32 v11, 6, v198
	v_and_b32_e32 v12, 32, v199
	v_lshlrev_b32_e32 v156, 14, v10
	v_and_b32_e32 v8, 0x3c0, v8
	s_addc_u32 s1, s1, s79
	v_mov_b32_e32 v2, 0
	v_lshlrev_b32_e32 v153, 13, v204
	v_bitop3_b32 v155, v11, v12, v9 bitop3:0x36
	v_lshlrev_b32_e32 v205, 7, v10
	v_or_b32_e32 v150, 0x800, v156
	v_bitop3_b32 v154, v8, v12, v9 bitop3:0x36
	v_or_b32_e32 v152, 0x1000, v156
	v_or_b32_e32 v151, 0x1800, v156
	v_or_b32_e32 v149, 0x2000, v156
	v_or_b32_e32 v148, 0x2800, v156
	v_or_b32_e32 v147, 0x3000, v156
	v_or_b32_e32 v146, 0x3800, v156
	v_lshl_add_u64 v[138:139], s[0:1], 0, v[178:179]
	v_lshl_add_u64 v[140:141], s[0:1], 0, v[180:181]
	v_lshl_add_u64 v[142:143], s[0:1], 0, v[194:195]
	v_lshl_add_u64 v[144:145], s[0:1], 0, v[196:197]
	s_mov_b64 s[0:1], 0
	s_mov_b32 s56, 0
	v_add_u32_e32 v244, 0x10000, v185
	s_nop 0
	v_readfirstlane_b32 s58, v244
	s_mov_b32 m0, s58
	v_lshl_add_u64 v[208:209], v[130:131], 0, s[0:1]
	global_load_lds_dwordx4 v[208:209], off
	s_add_u32 m0, s58, 0x8000
	v_lshl_add_u64 v[208:209], v[138:139], 0, s[0:1]
	global_load_lds_dwordx4 v[208:209], off
	s_add_u32 m0, s58, 0x2000
	v_lshl_add_u64 v[208:209], v[132:133], 0, s[0:1]
	global_load_lds_dwordx4 v[208:209], off
	s_add_u32 m0, s58, 0xa000
	v_lshl_add_u64 v[208:209], v[140:141], 0, s[0:1]
	global_load_lds_dwordx4 v[208:209], off
	s_add_u32 m0, s58, 0x4000
	v_lshl_add_u64 v[208:209], v[134:135], 0, s[0:1]
	global_load_lds_dwordx4 v[208:209], off
	s_add_u32 m0, s58, 0xc000
	v_lshl_add_u64 v[208:209], v[142:143], 0, s[0:1]
	global_load_lds_dwordx4 v[208:209], off
	s_add_u32 m0, s58, 0x6000
	v_lshl_add_u64 v[208:209], v[136:137], 0, s[0:1]
	global_load_lds_dwordx4 v[208:209], off
	s_add_u32 m0, s58, 0xe000
	v_lshl_add_u64 v[208:209], v[144:145], 0, s[0:1]
	global_load_lds_dwordx4 v[208:209], off
	v_mov_b32_e32 v3, v2
	v_mov_b32_e32 v4, v2
	v_mov_b32_e32 v5, v2
	v_mov_b32_e32 v6, v2
	v_mov_b32_e32 v7, v2
	v_mov_b32_e32 v8, v2
	v_mov_b32_e32 v9, v2
	v_mov_b32_e32 v10, v2
	v_mov_b32_e32 v11, v2
	v_mov_b32_e32 v12, v2
	v_mov_b32_e32 v13, v2
	v_mov_b32_e32 v14, v2
	v_mov_b32_e32 v15, v2
	v_mov_b32_e32 v16, v2
	v_mov_b32_e32 v17, v2
	v_mov_b32_e32 v18, v2
	v_mov_b32_e32 v19, v2
	v_mov_b32_e32 v20, v2
	v_mov_b32_e32 v21, v2
	v_mov_b32_e32 v22, v2
	v_mov_b32_e32 v23, v2
	v_mov_b32_e32 v24, v2
	v_mov_b32_e32 v25, v2
	v_mov_b32_e32 v26, v2
	v_mov_b32_e32 v27, v2
	v_mov_b32_e32 v28, v2
	v_mov_b32_e32 v29, v2
	v_mov_b32_e32 v30, v2
	v_mov_b32_e32 v31, v2
	v_mov_b32_e32 v32, v2
	v_mov_b32_e32 v33, v2
	v_mov_b32_e32 v34, v2
	v_mov_b32_e32 v35, v2
	v_mov_b32_e32 v36, v2
	v_mov_b32_e32 v37, v2
	v_mov_b32_e32 v38, v2
	v_mov_b32_e32 v39, v2
	v_mov_b32_e32 v40, v2
	v_mov_b32_e32 v41, v2
	v_mov_b32_e32 v42, v2
	v_mov_b32_e32 v43, v2
	v_mov_b32_e32 v44, v2
	v_mov_b32_e32 v45, v2
	v_mov_b32_e32 v46, v2
	v_mov_b32_e32 v47, v2
	v_mov_b32_e32 v48, v2
	v_mov_b32_e32 v49, v2
	v_mov_b32_e32 v50, v2
	v_mov_b32_e32 v51, v2
	v_mov_b32_e32 v52, v2
	v_mov_b32_e32 v53, v2
	v_mov_b32_e32 v54, v2
	v_mov_b32_e32 v55, v2
	v_mov_b32_e32 v56, v2
	v_mov_b32_e32 v57, v2
	v_mov_b32_e32 v58, v2
	v_mov_b32_e32 v59, v2
	v_mov_b32_e32 v60, v2
	v_mov_b32_e32 v61, v2
	v_mov_b32_e32 v62, v2
	v_mov_b32_e32 v63, v2
	v_mov_b32_e32 v64, v2
	v_mov_b32_e32 v65, v2
	v_mov_b32_e32 v66, v2
	v_mov_b32_e32 v67, v2
	v_mov_b32_e32 v68, v2
	v_mov_b32_e32 v69, v2
	v_mov_b32_e32 v70, v2
	v_mov_b32_e32 v71, v2
	v_mov_b32_e32 v72, v2
	v_mov_b32_e32 v73, v2
	v_mov_b32_e32 v74, v2
	v_mov_b32_e32 v75, v2
	v_mov_b32_e32 v76, v2
	v_mov_b32_e32 v77, v2
	v_mov_b32_e32 v78, v2
	v_mov_b32_e32 v79, v2
	v_mov_b32_e32 v80, v2
	v_mov_b32_e32 v81, v2
	v_mov_b32_e32 v82, v2
	v_mov_b32_e32 v83, v2
	v_mov_b32_e32 v84, v2
	v_mov_b32_e32 v85, v2
	v_mov_b32_e32 v86, v2
	v_mov_b32_e32 v87, v2
	v_mov_b32_e32 v88, v2
	v_mov_b32_e32 v89, v2
	v_mov_b32_e32 v90, v2
	v_mov_b32_e32 v91, v2
	v_mov_b32_e32 v92, v2
	v_mov_b32_e32 v93, v2
	v_mov_b32_e32 v94, v2
	v_mov_b32_e32 v95, v2
	v_mov_b32_e32 v96, v2
	v_mov_b32_e32 v97, v2
	v_mov_b32_e32 v98, v2
	v_mov_b32_e32 v99, v2
	v_mov_b32_e32 v100, v2
	v_mov_b32_e32 v101, v2
	v_mov_b32_e32 v102, v2
	v_mov_b32_e32 v103, v2
	v_mov_b32_e32 v104, v2
	v_mov_b32_e32 v105, v2
	v_mov_b32_e32 v106, v2
	v_mov_b32_e32 v107, v2
	v_mov_b32_e32 v108, v2
	v_mov_b32_e32 v109, v2
	v_mov_b32_e32 v110, v2
	v_mov_b32_e32 v111, v2
	v_mov_b32_e32 v112, v2
	v_mov_b32_e32 v113, v2
	v_mov_b32_e32 v114, v2
	v_mov_b32_e32 v115, v2
	v_mov_b32_e32 v116, v2
	v_mov_b32_e32 v117, v2
	v_mov_b32_e32 v118, v2
	v_mov_b32_e32 v119, v2
	v_mov_b32_e32 v120, v2
	v_mov_b32_e32 v121, v2
	v_mov_b32_e32 v122, v2
	v_mov_b32_e32 v123, v2
	v_mov_b32_e32 v124, v2
	v_mov_b32_e32 v125, v2
	v_mov_b32_e32 v126, v2
	v_mov_b32_e32 v127, v2
	v_mov_b32_e32 v128, v2
	v_mov_b32_e32 v129, v2
	s_mov_b32 s58, 0
	v_add3_u32 v0, s58, v155, v153
	v_add3_u32 v157, s58, v155, v156
	v_add3_u32 v238, s58, v154, v152
	v_add3_u32 v240, s58, v154, v149
	v_add3_u32 v242, s58, v154, v147
	v_add3_u32 v207, s58, v154, v150
	v_add3_u32 v239, s58, v154, v151
	v_add3_u32 v241, s58, v154, v148
	v_add3_u32 v243, s58, v154, v146
	ds_read_b128 v[158:161], v0 offset:32768
	ds_read_b128 v[162:165], v0 offset:34816
	ds_read_b128 v[174:177], v157
	ds_read_b128 v[186:189], v207
	ds_read_b128 v[190:193], v238
	ds_read_b128 v[212:215], v239
	ds_read_b128 v[222:225], v240
	ds_read_b128 v[226:229], v241
	ds_read_b128 v[230:233], v242
	ds_read_b128 v[234:237], v243
	ds_read_b128 v[166:169], v0 offset:36864
	ds_read_b128 v[170:173], v0 offset:38912

; DI void g8_decode(int u, int x, int nN, int& pm, int& pn) {
;   const int ng = u >> 6, rem = u & 63;
;   int gn = nN - 4 * ng; if (gn > 4) gn = 4;
;   const int mg = rem / (8 * gn), jj = rem % (8 * gn);
;   pm = 16 * x + 8 * mg + (jj & 7); pn = 4 * ng + (jj >> 3);
; }
; template <class Epi>
; DI void gemm8_phase(int x, int j, const bf16_t* __restrict__ A, int lda, const bf16_t* __restrict__ Bt, int K, int N, int a_grp, const Epi epi) {
;     ...
;   for (int u = j; u < total; u += nb) {
;     int pm, pn; g8_decode(u, x, nN, pm, pn);
;     const int brow = pm * 256, bcol = pn * 256;
;     const bf16_t* Ab = A + (size_t)brow * lda + (a_grp ? (bcol / a_grp) * K : 0);
;     const bf16_t* Bb = Bt + (size_t)bcol * ldb;
;     const bool has_next = (u + nb < total);
;     const bf16_t* Abn = Ab; const bf16_t* Bbn = Bb;
;     if (has_next) {
;       int pm2, pn2; g8_decode(u + nb, x, nN, pm2, pn2);
;       Abn = A + (size_t)(pm2 * 256) * lda + (a_grp ? ((pn2 * 256) / a_grp) * K : 0);
;       Bbn = Bt + (size_t)(pn2 * 256) * ldb;
;     }
.LBB0_645:
	s_ashr_i32 s3, s58, 4
	s_and_b32 s3, s3, -4
	s_sub_i32 s8, 5, s3
	s_min_i32 s8, s8, 4
	s_lshl_b32 s9, s8, 3
	s_ashr_i32 s31, s8, 31
	s_abs_i32 s8, s9
	s_and_b32 s2, s58, 63
	s_ff1_i32_b32 s11, s8
	s_lshr_b32 s8, s2, s11
	s_xor_b32 s59, s8, s31
	s_sub_i32 s8, s59, s31
	s_mul_i32 s9, s8, s9
	s_sub_i32 s2, s2, s9
	s_lshl_b32 s8, s8, 3
	s_add_i32 s8, s8, s28
	s_and_b32 s78, s2, 7
	s_lshr_b32 s2, s2, 3
	s_or_b32 s8, s8, s78
	s_add_i32 s9, s2, s3
	s_lshl_b32 s2, s8, 8
	s_lshl_b32 s3, s9, 8
	s_mul_i32 s8, s8, 0x88000
	s_mul_hi_i32 s10, s2, 0x880
	s_add_u32 s14, s50, s8
	s_addc_u32 s15, s51, s10
	s_mul_i32 s79, s9, 0x88000
	s_mul_hi_i32 s81, s3, 0x880
	s_add_u32 s38, s54, s79
	s_addc_u32 s39, s55, s81
	s_add_i32 s58, s58, s33
	s_cmpk_lt_i32 s58, 0x50
	s_cselect_b64 s[12:13], -1, 0
	s_cmpk_gt_i32 s58, 0x4f
	s_cselect_b64 s[74:75], -1, 0
	s_and_b64 vcc, exec, s[74:75]
	s_mov_b64 s[8:9], s[14:15]
	s_mov_b64 s[10:11], s[38:39]
	s_cbranch_vccnz .LBB0_647
	s_ashr_i32 s8, s58, 4
	s_and_b32 s8, s8, -4
	s_sub_i32 s9, 5, s8
	s_min_i32 s9, s9, 4
	s_lshl_b32 s10, s9, 3
	s_abs_i32 s11, s10
	s_and_b32 s87, s58, 63
	s_ashr_i32 s9, s9, 31
	s_ff1_i32_b32 s92, s11
	s_lshr_b32 s11, s87, s92
	s_xor_b32 s11, s11, s9
	s_sub_i32 s9, s11, s9
	s_mul_i32 s10, s9, s10
	s_lshl_b32 s9, s9, 3
	s_sub_i32 s10, s87, s10
	s_add_i32 s9, s9, s28
	s_and_b32 s11, s10, 7
	s_lshr_b32 s10, s10, 3
	s_or_b32 s9, s9, s11
	s_add_i32 s10, s10, s8
	s_lshl_b32 s8, s9, 8
	s_mul_i32 s9, s9, 0x88000
	s_mul_hi_i32 s11, s8, 0x880
	s_add_u32 s8, s50, s9
	s_addc_u32 s9, s51, s11
	s_lshl_b32 s11, s10, 8
	s_mul_i32 s10, s10, 0x88000
	s_mul_hi_i32 s11, s11, 0x880
	s_add_u32 s10, s54, s10
	s_mov_b32 s92, 0x10000
	s_addc_u32 s11, s55, s11

; DI int opaque_tid512() { int t = threadIdx.x; asm volatile("" : "+v"(t)); return t; }
; #define G8_STAGE(buf_, ap_, bp_) G8_STAGE_R(buf_, ap_, bp_, 0, 4)
; template <class Epi>
; DI void gemm8_tile(const bf16_t* __restrict__ Ab, int lda, const bf16_t* __restrict__ Bb, int ldb, int K, int brow, int bcol, const Epi epi,
;                    bool staged, bool has_next, const bf16_t* __restrict__ Abn, const bf16_t* __restrict__ Bbn) {
;   const int tid = opaque_tid512(), wid = tid >> 6, lane = tid & 63, wr = wid >> 2, wc = wid & 3, fr = lane & 15, fq = lane >> 4;
;   unsigned aoff[4], boff[4];
; #pragma unroll
;   for (int i = 0; i < 4; ++i) { int R, C; stage_rc2(wid * 1024 + i * 8192 + lane * 16, R, C); aoff[i] = (unsigned)R * (unsigned)lda + (unsigned)C; boff[i] = (unsigned)R * (unsigned)ldb + (unsigned)C; }
;     ...
;   f32x4 acc[8][4];
; #pragma unroll
;   for (int m = 0; m < 8; ++m)
; #pragma unroll
;     for (int n = 0; n < 4; ++n) acc[m][n] = (f32x4){0.f, 0.f, 0.f, 0.f};
;   const int nt = K / 64;
;   if (!staged) {
;     G8_STAGE(0, Ab, Bb);
;     asm volatile("s_waitcnt vmcnt(0)" ::: "memory");
;     __syncthreads();
;   }
;   for (int t = 0; t < nt; ++t) {
;     const int cur = t & 1;
;     const unsigned char* sa = smem + cur * G8_STAGE_B;
;     const unsigned char* sb = sa + G8_TILE_B;
; #pragma unroll
;     for (int ks = 0; ks < 2; ++ks) {
;       bf16x8 At[8], Bf[4];
;       Bf[0] = *(const bf16x8*)(sb + lds_byte2(wc * 64 + fr, ks * 32 + fq * 8));
;       At[0] = *(const bf16x8*)(sa + lds_byte2(wr * 128 + fr, ks * 32 + fq * 8));
; #pragma unroll
;       for (int n = 1; n < 4; ++n) Bf[n] = *(const bf16x8*)(sb + lds_byte2(wc * 64 + n * 16 + fr, ks * 32 + fq * 8));
; #pragma unroll
;       for (int m = 1; m < 8; ++m) At[m] = *(const bf16x8*)(sa + lds_byte2(wr * 128 + m * 16 + fr, ks * 32 + fq * 8));
;       {
;         __builtin_amdgcn_sched_barrier(0);
;         if (t + 1 < nt) { G8_STAGE_R(cur ^ 1, Ab + (t + 1) * 64, Bb + (t + 1) * 64, 2 * ks, 2 * ks + 2); }
;         else if (has_next) { G8_STAGE_R(0, Abn, Bbn, 2 * ks, 2 * ks + 2); }
.LBB0_649:
	s_add_u32 s0, s56, s79
	v_lshlrev_b64 v[190:191], 1, v[0:1]
	s_addc_u32 s1, s57, s81
	v_lshlrev_b64 v[192:193], 1, v[6:7]
	v_lshlrev_b64 v[178:179], 1, v[4:5]
	v_lshlrev_b64 v[180:181], 1, v[2:3]
	v_lshl_add_u64 v[130:131], s[0:1], 0, v[190:191]
	v_lshl_add_u64 v[132:133], s[0:1], 0, v[192:193]
	v_lshl_add_u64 v[134:135], s[0:1], 0, v[178:179]
	v_lshl_add_u64 v[136:137], s[0:1], 0, v[180:181]
	s_lshl_b32 s0, s59, 3
	s_add_i32 s0, s28, s0
	s_add_i32 s0, s0, s78
	s_lshl_b32 s1, s31, 3
	s_sub_i32 s0, s0, s1
	v_and_b32_e32 v200, 3, v8
	v_ashrrev_i32_e32 v8, 8, v195
	s_lshl_b32 s1, s0, 8
	s_mul_i32 s0, s0, 0x88000
	v_readlane_b32 s4, v253, 6
	v_and_b32_e32 v194, 15, v195
	v_lshlrev_b32_e32 v11, 2, v195
	v_lshlrev_b32_e32 v201, 7, v8
	v_lshlrev_b32_e32 v156, 14, v8
	v_lshlrev_b32_e32 v8, 6, v195
	s_mul_hi_i32 s1, s1, 0x880
	s_add_u32 s0, s4, s0
	v_readlane_b32 s4, v253, 7
	v_and_b32_e32 v9, 48, v195
	v_lshlrev_b32_e32 v10, 6, v194
	v_and_b32_e32 v11, 32, v11
	v_and_b32_e32 v8, 0x3c0, v8
	s_addc_u32 s1, s4, s1
	v_mov_b32_e32 v2, 0
	v_lshlrev_b32_e32 v153, 13, v200
	v_bitop3_b32 v155, v10, v11, v9 bitop3:0x36
	v_or_b32_e32 v150, 0x800, v156
	v_bitop3_b32 v154, v8, v11, v9 bitop3:0x36
	v_or_b32_e32 v152, 0x1000, v156
	v_or_b32_e32 v151, 0x1800, v156
	v_or_b32_e32 v149, 0x2000, v156
	v_or_b32_e32 v148, 0x2800, v156
	v_or_b32_e32 v147, 0x3000, v156
	v_or_b32_e32 v146, 0x3800, v156
	v_lshl_add_u64 v[138:139], s[0:1], 0, v[190:191]
	v_lshl_add_u64 v[140:141], s[0:1], 0, v[192:193]
	v_lshl_add_u64 v[142:143], s[0:1], 0, v[178:179]
	v_lshl_add_u64 v[144:145], s[0:1], 0, v[180:181]
	s_mov_b64 s[0:1], 0
	s_mov_b32 s14, 0
	v_add_u32_e32 v243, 0x10000, v185
	s_nop 0
	v_readfirstlane_b32 s31, v243
	s_mov_b32 m0, s31
	v_lshl_add_u64 v[234:235], v[144:145], 0, s[0:1]
	global_load_lds_dwordx4 v[234:235], off
	s_add_u32 m0, s31, 0x8000
	v_lshl_add_u64 v[234:235], v[136:137], 0, s[0:1]
	global_load_lds_dwordx4 v[234:235], off
	s_add_u32 m0, s31, 0x2000
	v_lshl_add_u64 v[234:235], v[142:143], 0, s[0:1]
	global_load_lds_dwordx4 v[234:235], off
	s_add_u32 m0, s31, 0xa000
	v_lshl_add_u64 v[234:235], v[134:135], 0, s[0:1]
	global_load_lds_dwordx4 v[234:235], off
	s_add_u32 m0, s31, 0x4000
	v_lshl_add_u64 v[234:235], v[140:141], 0, s[0:1]
	global_load_lds_dwordx4 v[234:235], off
	s_add_u32 m0, s31, 0xc000
	v_lshl_add_u64 v[234:235], v[132:133], 0, s[0:1]
	global_load_lds_dwordx4 v[234:235], off
	s_add_u32 m0, s31, 0x6000
	v_lshl_add_u64 v[234:235], v[138:139], 0, s[0:1]
	global_load_lds_dwordx4 v[234:235], off
	s_add_u32 m0, s31, 0xe000
	v_lshl_add_u64 v[234:235], v[130:131], 0, s[0:1]
	global_load_lds_dwordx4 v[234:235], off
	v_mov_b32_e32 v3, v2
	v_mov_b32_e32 v4, v2
	v_mov_b32_e32 v5, v2
	v_mov_b32_e32 v6, v2
	v_mov_b32_e32 v7, v2
	v_mov_b32_e32 v8, v2
	v_mov_b32_e32 v9, v2
	v_mov_b32_e32 v10, v2
	v_mov_b32_e32 v11, v2
	v_mov_b32_e32 v12, v2
	v_mov_b32_e32 v13, v2
	v_mov_b32_e32 v14, v2
	v_mov_b32_e32 v15, v2
	v_mov_b32_e32 v16, v2
	v_mov_b32_e32 v17, v2
	v_mov_b32_e32 v18, v2
	v_mov_b32_e32 v19, v2
	v_mov_b32_e32 v20, v2
	v_mov_b32_e32 v21, v2
	v_mov_b32_e32 v22, v2
	v_mov_b32_e32 v23, v2
	v_mov_b32_e32 v24, v2
	v_mov_b32_e32 v25, v2
	v_mov_b32_e32 v26, v2
	v_mov_b32_e32 v27, v2
	v_mov_b32_e32 v28, v2
	v_mov_b32_e32 v29, v2
	v_mov_b32_e32 v30, v2
	v_mov_b32_e32 v31, v2
	v_mov_b32_e32 v32, v2
	v_mov_b32_e32 v33, v2
	v_mov_b32_e32 v34, v2
	v_mov_b32_e32 v35, v2
	v_mov_b32_e32 v36, v2
	v_mov_b32_e32 v37, v2
	v_mov_b32_e32 v38, v2
	v_mov_b32_e32 v39, v2
	v_mov_b32_e32 v40, v2
	v_mov_b32_e32 v41, v2
	v_mov_b32_e32 v42, v2
	v_mov_b32_e32 v43, v2
	v_mov_b32_e32 v44, v2
	v_mov_b32_e32 v45, v2
	v_mov_b32_e32 v46, v2
	v_mov_b32_e32 v47, v2
	v_mov_b32_e32 v48, v2
	v_mov_b32_e32 v49, v2
	v_mov_b32_e32 v50, v2
	v_mov_b32_e32 v51, v2
	v_mov_b32_e32 v52, v2
	v_mov_b32_e32 v53, v2
	v_mov_b32_e32 v54, v2
	v_mov_b32_e32 v55, v2
	v_mov_b32_e32 v56, v2
	v_mov_b32_e32 v57, v2
	v_mov_b32_e32 v58, v2
	v_mov_b32_e32 v59, v2
	v_mov_b32_e32 v60, v2
	v_mov_b32_e32 v61, v2
	v_mov_b32_e32 v62, v2
	v_mov_b32_e32 v63, v2
	v_mov_b32_e32 v64, v2
	v_mov_b32_e32 v65, v2
	v_mov_b32_e32 v66, v2
	v_mov_b32_e32 v67, v2
	v_mov_b32_e32 v68, v2
	v_mov_b32_e32 v69, v2
	v_mov_b32_e32 v70, v2
	v_mov_b32_e32 v71, v2
	v_mov_b32_e32 v72, v2
	v_mov_b32_e32 v73, v2
	v_mov_b32_e32 v74, v2
	v_mov_b32_e32 v75, v2
	v_mov_b32_e32 v76, v2
	v_mov_b32_e32 v77, v2
	v_mov_b32_e32 v78, v2
	v_mov_b32_e32 v79, v2
	v_mov_b32_e32 v80, v2
	v_mov_b32_e32 v81, v2
	v_mov_b32_e32 v82, v2
	v_mov_b32_e32 v83, v2
	v_mov_b32_e32 v84, v2
	v_mov_b32_e32 v85, v2
	v_mov_b32_e32 v86, v2
	v_mov_b32_e32 v87, v2
	v_mov_b32_e32 v88, v2
	v_mov_b32_e32 v89, v2
	v_mov_b32_e32 v90, v2
	v_mov_b32_e32 v91, v2
	v_mov_b32_e32 v92, v2
	v_mov_b32_e32 v93, v2
	v_mov_b32_e32 v94, v2
	v_mov_b32_e32 v95, v2
	v_mov_b32_e32 v96, v2
	v_mov_b32_e32 v97, v2
	v_mov_b32_e32 v98, v2
	v_mov_b32_e32 v99, v2
	v_mov_b32_e32 v100, v2
	v_mov_b32_e32 v101, v2
	v_mov_b32_e32 v102, v2
	v_mov_b32_e32 v103, v2
	v_mov_b32_e32 v104, v2
	v_mov_b32_e32 v105, v2
	v_mov_b32_e32 v106, v2
	v_mov_b32_e32 v107, v2
	v_mov_b32_e32 v108, v2
	v_mov_b32_e32 v109, v2
	v_mov_b32_e32 v110, v2
	v_mov_b32_e32 v111, v2
	v_mov_b32_e32 v112, v2
	v_mov_b32_e32 v113, v2
	v_mov_b32_e32 v114, v2
	v_mov_b32_e32 v115, v2
	v_mov_b32_e32 v116, v2
	v_mov_b32_e32 v117, v2
	v_mov_b32_e32 v118, v2
	v_mov_b32_e32 v119, v2
	v_mov_b32_e32 v120, v2
	v_mov_b32_e32 v121, v2
	v_mov_b32_e32 v122, v2
	v_mov_b32_e32 v123, v2
	v_mov_b32_e32 v124, v2
	v_mov_b32_e32 v125, v2
	v_mov_b32_e32 v126, v2
	v_mov_b32_e32 v127, v2
	v_mov_b32_e32 v128, v2
	v_mov_b32_e32 v129, v2
	s_mov_b32 s31, 0
	v_add3_u32 v0, s31, v155, v153
	v_add3_u32 v157, s31, v155, v156
	v_add3_u32 v237, s31, v154, v152
	v_add3_u32 v239, s31, v154, v149
	v_add3_u32 v241, s31, v154, v147
	v_add3_u32 v236, s31, v154, v150
	v_add3_u32 v238, s31, v154, v151
	v_add3_u32 v240, s31, v154, v148
	v_add3_u32 v242, s31, v154, v146
	ds_read_b128 v[158:161], v0 offset:32768
	ds_read_b128 v[162:165], v0 offset:34816
	ds_read_b128 v[174:177], v157
	ds_read_b128 v[186:189], v236
	ds_read_b128 v[202:205], v237
	ds_read_b128 v[206:209], v238
	ds_read_b128 v[212:215], v239
	ds_read_b128 v[222:225], v240
	ds_read_b128 v[226:229], v241
	ds_read_b128 v[230:233], v242
	ds_read_b128 v[166:169], v0 offset:36864
	ds_read_b128 v[170:173], v0 offset:38912

; DI void g8_decode(int u, int x, int nN, int& pm, int& pn) {
;   const int ng = u >> 6, rem = u & 63;
;   int gn = nN - 4 * ng; if (gn > 4) gn = 4;
;   const int mg = rem / (8 * gn), jj = rem % (8 * gn);
;   pm = 16 * x + 8 * mg + (jj & 7); pn = 4 * ng + (jj >> 3);
; }
; template <class Epi>
; DI void gemm8_phase(int x, int j, const bf16_t* __restrict__ A, int lda, const bf16_t* __restrict__ Bt, int K, int N, int a_grp, const Epi epi) {
;     ...
;   for (int u = j; u < total; u += nb) {
;     int pm, pn; g8_decode(u, x, nN, pm, pn);
;     const int brow = pm * 256, bcol = pn * 256;
;     const bf16_t* Ab = A + (size_t)brow * lda + (a_grp ? (bcol / a_grp) * K : 0);
;     const bf16_t* Bb = Bt + (size_t)bcol * ldb;
;     const bool has_next = (u + nb < total);
;     const bf16_t* Abn = Ab; const bf16_t* Bbn = Bb;
;     if (has_next) {
;       int pm2, pn2; g8_decode(u + nb, x, nN, pm2, pn2);
;       Abn = A + (size_t)(pm2 * 256) * lda + (a_grp ? ((pn2 * 256) / a_grp) * K : 0);
;       Bbn = Bt + (size_t)(pn2 * 256) * ldb;
;     }
.LBB0_1249:
	s_ashr_i32 s9, s59, 4
	s_and_b32 s9, s9, -4
	s_sub_i32 s10, 6, s9
	s_min_i32 s10, s10, 4
	s_lshl_b32 s11, s10, 3
	s_ashr_i32 s75, s10, 31
	s_abs_i32 s10, s11
	s_and_b32 s8, s59, 63
	s_ff1_i32_b32 s13, s10
	s_lshr_b32 s10, s8, s13
	s_xor_b32 s78, s10, s75
	s_sub_i32 s10, s78, s75
	s_mul_i32 s11, s10, s11
	s_sub_i32 s8, s8, s11
	s_lshl_b32 s10, s10, 3
	s_add_i32 s10, s10, s28
	s_and_b32 s79, s8, 7
	s_lshr_b32 s8, s8, 3
	s_or_b32 s10, s10, s79
	s_add_i32 s8, s8, s9
	s_lshl_b32 s31, s10, 8
	s_lshl_b32 s74, s8, 8
	s_mul_i32 s10, s10, 0x88000
	s_mul_hi_i32 s9, s31, 0x880
	s_add_u32 s38, s52, s10
	s_addc_u32 s39, s53, s9
	s_mul_i32 s81, s8, 0x68000
	s_mul_hi_i32 s87, s74, 0x680
	s_add_u32 s54, s2, s81
	s_addc_u32 s55, s3, s87
	s_add_i32 s59, s59, s33
	s_cmpk_lt_i32 s59, 0x60
	s_cselect_b64 s[14:15], -1, 0
	s_cmpk_gt_i32 s59, 0x5f
	s_cselect_b64 s[8:9], -1, 0
	s_and_b64 vcc, exec, s[8:9]
	s_mov_b64 s[10:11], s[38:39]
	s_mov_b64 s[12:13], s[54:55]
	s_cbranch_vccnz .LBB0_1251
	s_ashr_i32 s10, s59, 4
	s_and_b32 s10, s10, -4
	s_sub_i32 s11, 6, s10
	s_min_i32 s11, s11, 4
	s_lshl_b32 s12, s11, 3
	s_abs_i32 s13, s12
	s_and_b32 s90, s59, 63
	s_ashr_i32 s11, s11, 31
	s_ff1_i32_b32 vcc_lo, s13
	s_lshr_b32 s13, s90, vcc_lo
	s_xor_b32 s13, s13, s11
	s_sub_i32 s11, s13, s11
	s_mul_i32 s12, s11, s12
	s_lshl_b32 s11, s11, 3
	s_sub_i32 s12, s90, s12
	s_add_i32 s11, s11, s28
	s_and_b32 s13, s12, 7
	s_lshr_b32 s12, s12, 3
	s_or_b32 s11, s11, s13
	s_add_i32 s12, s12, s10
	s_lshl_b32 s10, s11, 8
	s_mul_i32 s11, s11, 0x88000
	s_mul_hi_i32 s13, s10, 0x880
	s_add_u32 s10, s52, s11
	s_addc_u32 s11, s53, s13
	s_lshl_b32 s13, s12, 8
	s_mul_i32 s12, s12, 0x68000
	s_mul_hi_i32 s13, s13, 0x680
	s_add_u32 s12, s2, s12
	s_mov_b32 s92, 0x10000
	s_addc_u32 s13, s3, s13

; DI int opaque_tid512() { int t = threadIdx.x; asm volatile("" : "+v"(t)); return t; }
; #define G8_STAGE(buf_, ap_, bp_) G8_STAGE_R(buf_, ap_, bp_, 0, 4)
; template <class Epi>
; DI void gemm8_tile(const bf16_t* __restrict__ Ab, int lda, const bf16_t* __restrict__ Bb, int ldb, int K, int brow, int bcol, const Epi epi,
;                    bool staged, bool has_next, const bf16_t* __restrict__ Abn, const bf16_t* __restrict__ Bbn) {
;   const int tid = opaque_tid512(), wid = tid >> 6, lane = tid & 63, wr = wid >> 2, wc = wid & 3, fr = lane & 15, fq = lane >> 4;
;   unsigned aoff[4], boff[4];
; #pragma unroll
;   for (int i = 0; i < 4; ++i) { int R, C; stage_rc2(wid * 1024 + i * 8192 + lane * 16, R, C); aoff[i] = (unsigned)R * (unsigned)lda + (unsigned)C; boff[i] = (unsigned)R * (unsigned)ldb + (unsigned)C; }
;     ...
;   f32x4 acc[8][4];
; #pragma unroll
;   for (int m = 0; m < 8; ++m)
; #pragma unroll
;     for (int n = 0; n < 4; ++n) acc[m][n] = (f32x4){0.f, 0.f, 0.f, 0.f};
;   const int nt = K / 64;
;   if (!staged) {
;     G8_STAGE(0, Ab, Bb);
;     asm volatile("s_waitcnt vmcnt(0)" ::: "memory");
;     __syncthreads();
;   }
;   for (int t = 0; t < nt; ++t) {
;     const int cur = t & 1;
;     const unsigned char* sa = smem + cur * G8_STAGE_B;
;     const unsigned char* sb = sa + G8_TILE_B;
; #pragma unroll
;     for (int ks = 0; ks < 2; ++ks) {
;       bf16x8 At[8], Bf[4];
;       Bf[0] = *(const bf16x8*)(sb + lds_byte2(wc * 64 + fr, ks * 32 + fq * 8));
;       At[0] = *(const bf16x8*)(sa + lds_byte2(wr * 128 + fr, ks * 32 + fq * 8));
; #pragma unroll
;       for (int n = 1; n < 4; ++n) Bf[n] = *(const bf16x8*)(sb + lds_byte2(wc * 64 + n * 16 + fr, ks * 32 + fq * 8));
; #pragma unroll
;       for (int m = 1; m < 8; ++m) At[m] = *(const bf16x8*)(sa + lds_byte2(wr * 128 + m * 16 + fr, ks * 32 + fq * 8));
;       {
;         __builtin_amdgcn_sched_barrier(0);
;         if (t + 1 < nt) { G8_STAGE_R(cur ^ 1, Ab + (t + 1) * 64, Bb + (t + 1) * 64, 2 * ks, 2 * ks + 2); }
;         else if (has_next) { G8_STAGE_R(0, Abn, Bbn, 2 * ks, 2 * ks + 2); }
.LBB0_1253:
	s_add_u32 s0, s57, s81
	s_addc_u32 s1, s58, s87
	v_lshl_add_u64 v[130:131], v[0:1], 1, s[0:1]
	v_lshl_add_u64 v[132:133], v[180:181], 1, s[0:1]
	v_lshl_add_u64 v[134:135], v[190:191], 1, s[0:1]
	v_lshl_add_u64 v[136:137], v[186:187], 1, s[0:1]
	s_lshl_b32 s0, s78, 3
	s_add_i32 s0, s28, s0
	s_add_i32 s0, s0, s79
	s_lshl_b32 s1, s75, 3
	s_sub_i32 s0, s0, s1
	v_and_b32_e32 v198, 3, v3
	v_ashrrev_i32_e32 v3, 8, v2
	v_and_b32_e32 v197, 15, v2
	v_and_b32_e32 v4, 48, v2
	v_lshlrev_b32_e32 v6, 2, v2
	v_lshlrev_b32_e32 v2, 6, v2
	s_lshl_b32 s1, s0, 8
	s_mul_i32 s0, s0, 0x88000
	v_and_b32_e32 v6, 32, v6
	v_and_b32_e32 v2, 0x3c0, v2
	s_mul_hi_i32 s1, s1, 0x880
	s_add_u32 s0, s91, s0
	v_lshlrev_b32_e32 v5, 6, v197
	v_lshlrev_b32_e32 v156, 14, v3
	v_bitop3_b32 v154, v2, v6, v4 bitop3:0x36
	s_addc_u32 s1, s72, s1
	v_mov_b32_e32 v2, 0
	v_lshlrev_b32_e32 v153, 13, v198
	v_bitop3_b32 v155, v5, v6, v4 bitop3:0x36
	v_lshlrev_b32_e32 v199, 7, v3
	v_or_b32_e32 v150, 0x800, v156
	v_or_b32_e32 v152, 0x1000, v156
	v_or_b32_e32 v151, 0x1800, v156
	v_or_b32_e32 v149, 0x2000, v156
	v_or_b32_e32 v148, 0x2800, v156
	v_or_b32_e32 v147, 0x3000, v156
	v_or_b32_e32 v146, 0x3800, v156
	v_lshl_add_u64 v[138:139], v[182:183], 1, s[0:1]
	v_lshl_add_u64 v[140:141], v[178:179], 1, s[0:1]
	v_lshl_add_u64 v[142:143], v[188:189], 1, s[0:1]
	v_lshl_add_u64 v[144:145], v[184:185], 1, s[0:1]
	s_mov_b64 s[0:1], 0
	s_mov_b32 s38, 0
	v_add_u32_e32 v250, 0x10000, v203
	s_nop 0
	v_readfirstlane_b32 s54, v250
	s_mov_b32 m0, s54
	v_lshl_add_u64 v[208:209], v[144:145], 0, s[0:1]
	global_load_lds_dwordx4 v[208:209], off
	s_add_u32 m0, s54, 0x8000
	v_lshl_add_u64 v[208:209], v[136:137], 0, s[0:1]
	global_load_lds_dwordx4 v[208:209], off
	s_add_u32 m0, s54, 0x2000
	v_lshl_add_u64 v[208:209], v[142:143], 0, s[0:1]
	global_load_lds_dwordx4 v[208:209], off
	s_add_u32 m0, s54, 0xa000
	v_lshl_add_u64 v[208:209], v[134:135], 0, s[0:1]
	global_load_lds_dwordx4 v[208:209], off
	s_add_u32 m0, s54, 0x4000
	v_lshl_add_u64 v[208:209], v[140:141], 0, s[0:1]
	global_load_lds_dwordx4 v[208:209], off
	s_add_u32 m0, s54, 0xc000
	v_lshl_add_u64 v[208:209], v[132:133], 0, s[0:1]
	global_load_lds_dwordx4 v[208:209], off
	s_add_u32 m0, s54, 0x6000
	v_lshl_add_u64 v[208:209], v[138:139], 0, s[0:1]
	global_load_lds_dwordx4 v[208:209], off
	s_add_u32 m0, s54, 0xe000
	v_lshl_add_u64 v[208:209], v[130:131], 0, s[0:1]
	global_load_lds_dwordx4 v[208:209], off
	v_mov_b32_e32 v3, v2
	v_mov_b32_e32 v4, v2
	v_mov_b32_e32 v5, v2
	v_mov_b32_e32 v6, v2
	v_mov_b32_e32 v7, v2
	v_mov_b32_e32 v8, v2
	v_mov_b32_e32 v9, v2
	v_mov_b32_e32 v10, v2
	v_mov_b32_e32 v11, v2
	v_mov_b32_e32 v12, v2
	v_mov_b32_e32 v13, v2
	v_mov_b32_e32 v14, v2
	v_mov_b32_e32 v15, v2
	v_mov_b32_e32 v16, v2
	v_mov_b32_e32 v17, v2
	v_mov_b32_e32 v18, v2
	v_mov_b32_e32 v19, v2
	v_mov_b32_e32 v20, v2
	v_mov_b32_e32 v21, v2
	v_mov_b32_e32 v22, v2
	v_mov_b32_e32 v23, v2
	v_mov_b32_e32 v24, v2
	v_mov_b32_e32 v25, v2
	v_mov_b32_e32 v26, v2
	v_mov_b32_e32 v27, v2
	v_mov_b32_e32 v28, v2
	v_mov_b32_e32 v29, v2
	v_mov_b32_e32 v30, v2
	v_mov_b32_e32 v31, v2
	v_mov_b32_e32 v32, v2
	v_mov_b32_e32 v33, v2
	v_mov_b32_e32 v34, v2
	v_mov_b32_e32 v35, v2
	v_mov_b32_e32 v36, v2
	v_mov_b32_e32 v37, v2
	v_mov_b32_e32 v38, v2
	v_mov_b32_e32 v39, v2
	v_mov_b32_e32 v40, v2
	v_mov_b32_e32 v41, v2
	v_mov_b32_e32 v42, v2
	v_mov_b32_e32 v43, v2
	v_mov_b32_e32 v44, v2
	v_mov_b32_e32 v45, v2
	v_mov_b32_e32 v46, v2
	v_mov_b32_e32 v47, v2
	v_mov_b32_e32 v48, v2
	v_mov_b32_e32 v49, v2
	v_mov_b32_e32 v50, v2
	v_mov_b32_e32 v51, v2
	v_mov_b32_e32 v52, v2
	v_mov_b32_e32 v53, v2
	v_mov_b32_e32 v54, v2
	v_mov_b32_e32 v55, v2
	v_mov_b32_e32 v56, v2
	v_mov_b32_e32 v57, v2
	v_mov_b32_e32 v58, v2
	v_mov_b32_e32 v59, v2
	v_mov_b32_e32 v60, v2
	v_mov_b32_e32 v61, v2
	v_mov_b32_e32 v62, v2
	v_mov_b32_e32 v63, v2
	v_mov_b32_e32 v64, v2
	v_mov_b32_e32 v65, v2
	v_mov_b32_e32 v66, v2
	v_mov_b32_e32 v67, v2
	v_mov_b32_e32 v68, v2
	v_mov_b32_e32 v69, v2
	v_mov_b32_e32 v70, v2
	v_mov_b32_e32 v71, v2
	v_mov_b32_e32 v72, v2
	v_mov_b32_e32 v73, v2
	v_mov_b32_e32 v74, v2
	v_mov_b32_e32 v75, v2
	v_mov_b32_e32 v76, v2
	v_mov_b32_e32 v77, v2
	v_mov_b32_e32 v78, v2
	v_mov_b32_e32 v79, v2
	v_mov_b32_e32 v80, v2
	v_mov_b32_e32 v81, v2
	v_mov_b32_e32 v82, v2
	v_mov_b32_e32 v83, v2
	v_mov_b32_e32 v84, v2
	v_mov_b32_e32 v85, v2
	v_mov_b32_e32 v86, v2
	v_mov_b32_e32 v87, v2
	v_mov_b32_e32 v88, v2
	v_mov_b32_e32 v89, v2
	v_mov_b32_e32 v90, v2
	v_mov_b32_e32 v91, v2
	v_mov_b32_e32 v92, v2
	v_mov_b32_e32 v93, v2
	v_mov_b32_e32 v94, v2
	v_mov_b32_e32 v95, v2
	v_mov_b32_e32 v96, v2
	v_mov_b32_e32 v97, v2
	v_mov_b32_e32 v98, v2
	v_mov_b32_e32 v99, v2
	v_mov_b32_e32 v100, v2
	v_mov_b32_e32 v101, v2
	v_mov_b32_e32 v102, v2
	v_mov_b32_e32 v103, v2
	v_mov_b32_e32 v104, v2
	v_mov_b32_e32 v105, v2
	v_mov_b32_e32 v106, v2
	v_mov_b32_e32 v107, v2
	v_mov_b32_e32 v108, v2
	v_mov_b32_e32 v109, v2
	v_mov_b32_e32 v110, v2
	v_mov_b32_e32 v111, v2
	v_mov_b32_e32 v112, v2
	v_mov_b32_e32 v113, v2
	v_mov_b32_e32 v114, v2
	v_mov_b32_e32 v115, v2
	v_mov_b32_e32 v116, v2
	v_mov_b32_e32 v117, v2
	v_mov_b32_e32 v118, v2
	v_mov_b32_e32 v119, v2
	v_mov_b32_e32 v120, v2
	v_mov_b32_e32 v121, v2
	v_mov_b32_e32 v122, v2
	v_mov_b32_e32 v123, v2
	v_mov_b32_e32 v124, v2
	v_mov_b32_e32 v125, v2
	v_mov_b32_e32 v126, v2
	v_mov_b32_e32 v127, v2
	v_mov_b32_e32 v128, v2
	v_mov_b32_e32 v129, v2
	s_mov_b32 s54, 0
	v_add3_u32 v157, s54, v155, v153
	v_add3_u32 v242, s54, v155, v156
	v_add3_u32 v244, s54, v154, v152
	v_add3_u32 v246, s54, v154, v149
	v_add3_u32 v248, s54, v154, v147
	v_add3_u32 v243, s54, v154, v150
	v_add3_u32 v245, s54, v154, v151
	v_add3_u32 v247, s54, v154, v148
	v_add3_u32 v249, s54, v154, v146
	ds_read_b128 v[158:161], v157 offset:32768
	ds_read_b128 v[162:165], v157 offset:34816
	ds_read_b128 v[174:177], v242
	ds_read_b128 v[204:207], v243
	ds_read_b128 v[212:215], v244
	ds_read_b128 v[222:225], v245
	ds_read_b128 v[226:229], v246
	ds_read_b128 v[230:233], v247
	ds_read_b128 v[234:237], v248
	ds_read_b128 v[238:241], v249
	ds_read_b128 v[166:169], v157 offset:36864
	ds_read_b128 v[170:173], v157 offset:38912

; DI void g8_decode(int u, int x, int nN, int& pm, int& pn) {
;   const int ng = u >> 6, rem = u & 63;
;   int gn = nN - 4 * ng; if (gn > 4) gn = 4;
;   const int mg = rem / (8 * gn), jj = rem % (8 * gn);
;   pm = 16 * x + 8 * mg + (jj & 7); pn = 4 * ng + (jj >> 3);
; }
; template <class Epi>
; DI void gemm8_phase(int x, int j, const bf16_t* __restrict__ A, int lda, const bf16_t* __restrict__ Bt, int K, int N, int a_grp, const Epi epi) {
;     ...
;   for (int u = j; u < total; u += nb) {
;     int pm, pn; g8_decode(u, x, nN, pm, pn);
;     const int brow = pm * 256, bcol = pn * 256;
;     const bf16_t* Ab = A + (size_t)brow * lda + (a_grp ? (bcol / a_grp) * K : 0);
;     const bf16_t* Bb = Bt + (size_t)bcol * ldb;
;     const bool has_next = (u + nb < total);
;     const bf16_t* Abn = Ab; const bf16_t* Bbn = Bb;
;     if (has_next) {
;       int pm2, pn2; g8_decode(u + nb, x, nN, pm2, pn2);
;       Abn = A + (size_t)(pm2 * 256) * lda + (a_grp ? ((pn2 * 256) / a_grp) * K : 0);
;       Bbn = Bt + (size_t)(pn2 * 256) * ldb;
;     }
.LBB0_1307:
	s_ashr_i32 s9, s59, 4
	s_and_b32 s9, s9, -4
	s_sub_i32 s10, 4, s9
	s_min_i32 s10, s10, 4
	s_lshl_b32 s11, s10, 3
	s_ashr_i32 s71, s10, 31
	s_abs_i32 s10, s11
	s_and_b32 s8, s59, 63
	s_ff1_i32_b32 s13, s10
	s_lshr_b32 s10, s8, s13
	s_xor_b32 s74, s10, s71
	s_sub_i32 s10, s74, s71
	s_mul_i32 s11, s10, s11
	s_sub_i32 s8, s8, s11
	s_lshl_b32 s10, s10, 3
	s_add_i32 s10, s10, s28
	s_and_b32 s75, s8, 7
	s_lshr_b32 s8, s8, 3
	s_or_b32 s10, s10, s75
	s_add_i32 s8, s8, s9
	s_lshl_b32 s31, s10, 8
	s_lshl_b32 s70, s8, 8
	s_mul_i32 s10, s10, 0x88000
	s_mul_hi_i32 s9, s31, 0x880
	s_add_u32 s38, s52, s10
	s_addc_u32 s39, s53, s9
	s_mul_i32 s78, s8, 0x88000
	s_mul_hi_i32 s79, s70, 0x880
	s_add_u32 s54, s2, s78
	s_addc_u32 s55, s3, s79
	s_add_i32 s59, s59, s33
	s_cmp_lt_i32 s59, 64
	s_cselect_b64 s[14:15], -1, 0
	s_cmp_gt_i32 s59, 63
	s_cselect_b64 s[12:13], -1, 0
	s_and_b64 vcc, exec, s[12:13]
	s_mov_b64 s[8:9], s[38:39]
	s_mov_b64 s[10:11], s[54:55]
	s_cbranch_vccnz .LBB0_1309
	s_ashr_i32 s8, s59, 4
	s_and_b32 s8, s8, -4
	s_sub_i32 s9, 4, s8
	s_min_i32 s9, s9, 4
	s_lshl_b32 s10, s9, 3
	s_abs_i32 s11, s10
	s_and_b32 s81, s59, 63
	s_ashr_i32 s9, s9, 31
	s_ff1_i32_b32 s85, s11
	s_lshr_b32 s11, s81, s85
	s_xor_b32 s11, s11, s9
	s_sub_i32 s9, s11, s9
	s_mul_i32 s10, s9, s10
	s_lshl_b32 s9, s9, 3
	s_sub_i32 s10, s81, s10
	s_add_i32 s9, s9, s28
	s_and_b32 s11, s10, 7
	s_lshr_b32 s10, s10, 3
	s_or_b32 s9, s9, s11
	s_add_i32 s10, s10, s8
	s_lshl_b32 s8, s9, 8
	s_mul_i32 s9, s9, 0x88000
	s_mul_hi_i32 s11, s8, 0x880
	s_add_u32 s8, s52, s9
	s_addc_u32 s9, s53, s11
	s_lshl_b32 s11, s10, 8
	s_mul_i32 s10, s10, 0x88000
	s_mul_hi_i32 s11, s11, 0x880
	s_add_u32 s10, s2, s10
	s_addc_u32 s11, s3, s11

; DI int opaque_tid512() { int t = threadIdx.x; asm volatile("" : "+v"(t)); return t; }
; #define G8_STAGE(buf_, ap_, bp_) G8_STAGE_R(buf_, ap_, bp_, 0, 4)
; template <class Epi>
; DI void gemm8_tile(const bf16_t* __restrict__ Ab, int lda, const bf16_t* __restrict__ Bb, int ldb, int K, int brow, int bcol, const Epi epi,
;                    bool staged, bool has_next, const bf16_t* __restrict__ Abn, const bf16_t* __restrict__ Bbn) {
;   const int tid = opaque_tid512(), wid = tid >> 6, lane = tid & 63, wr = wid >> 2, wc = wid & 3, fr = lane & 15, fq = lane >> 4;
;   unsigned aoff[4], boff[4];
; #pragma unroll
;   for (int i = 0; i < 4; ++i) { int R, C; stage_rc2(wid * 1024 + i * 8192 + lane * 16, R, C); aoff[i] = (unsigned)R * (unsigned)lda + (unsigned)C; boff[i] = (unsigned)R * (unsigned)ldb + (unsigned)C; }
;     ...
;   f32x4 acc[8][4];
; #pragma unroll
;   for (int m = 0; m < 8; ++m)
; #pragma unroll
;     for (int n = 0; n < 4; ++n) acc[m][n] = (f32x4){0.f, 0.f, 0.f, 0.f};
;   const int nt = K / 64;
;   if (!staged) {
;     G8_STAGE(0, Ab, Bb);
;     asm volatile("s_waitcnt vmcnt(0)" ::: "memory");
;     __syncthreads();
;   }
;   for (int t = 0; t < nt; ++t) {
;     const int cur = t & 1;
;     const unsigned char* sa = smem + cur * G8_STAGE_B;
;     const unsigned char* sb = sa + G8_TILE_B;
; #pragma unroll
;     for (int ks = 0; ks < 2; ++ks) {
;       bf16x8 At[8], Bf[4];
;       Bf[0] = *(const bf16x8*)(sb + lds_byte2(wc * 64 + fr, ks * 32 + fq * 8));
;       At[0] = *(const bf16x8*)(sa + lds_byte2(wr * 128 + fr, ks * 32 + fq * 8));
; #pragma unroll
;       for (int n = 1; n < 4; ++n) Bf[n] = *(const bf16x8*)(sb + lds_byte2(wc * 64 + n * 16 + fr, ks * 32 + fq * 8));
; #pragma unroll
;       for (int m = 1; m < 8; ++m) At[m] = *(const bf16x8*)(sa + lds_byte2(wr * 128 + m * 16 + fr, ks * 32 + fq * 8));
;       {
;         __builtin_amdgcn_sched_barrier(0);
;         if (t + 1 < nt) { G8_STAGE_R(cur ^ 1, Ab + (t + 1) * 64, Bb + (t + 1) * 64, 2 * ks, 2 * ks + 2); }
;         else if (has_next) { G8_STAGE_R(0, Abn, Bbn, 2 * ks, 2 * ks + 2); }
.LBB0_1311:
	s_lshl_b32 s0, s74, 3
	s_add_i32 s0, s28, s0
	s_add_i32 s0, s0, s75
	s_lshl_b32 s1, s71, 3
	s_sub_i32 s0, s0, s1
	s_lshl_b32 s1, s0, 8
	s_mul_i32 s0, s0, 0x88000
	s_mul_hi_i32 s1, s1, 0x880
	s_add_u32 s0, s91, s0
	v_and_b32_e32 v198, 15, v8
	v_lshlrev_b64 v[178:179], 1, v[4:5]
	s_addc_u32 s1, s72, s1
	v_lshlrev_b64 v[180:181], 1, v[2:3]
	v_lshlrev_b64 v[194:195], 1, v[6:7]
	v_lshlrev_b64 v[196:197], 1, v[0:1]
	v_and_b32_e32 v206, 63, v8
	v_ashrrev_i32_e32 v10, 8, v8
	v_and_b32_e32 v204, 3, v9
	v_and_b32_e32 v9, 48, v8
	v_lshlrev_b32_e32 v199, 2, v198
	v_lshlrev_b32_e32 v8, 6, v8
	v_lshl_add_u64 v[130:131], s[0:1], 0, v[178:179]
	v_lshl_add_u64 v[132:133], s[0:1], 0, v[180:181]
	v_lshl_add_u64 v[134:135], s[0:1], 0, v[194:195]
	v_lshl_add_u64 v[136:137], s[0:1], 0, v[196:197]
	s_add_u32 s0, s57, s78
	v_lshlrev_b32_e32 v11, 6, v198
	v_and_b32_e32 v12, 32, v199
	v_lshlrev_b32_e32 v156, 14, v10
	v_and_b32_e32 v8, 0x3c0, v8
	s_addc_u32 s1, s58, s79
	v_mov_b32_e32 v2, 0
	v_lshlrev_b32_e32 v153, 13, v204
	v_bitop3_b32 v155, v11, v12, v9 bitop3:0x36
	v_lshlrev_b32_e32 v205, 7, v10
	v_or_b32_e32 v150, 0x800, v156
	v_bitop3_b32 v154, v8, v12, v9 bitop3:0x36
	v_or_b32_e32 v152, 0x1000, v156
	v_or_b32_e32 v151, 0x1800, v156
	v_or_b32_e32 v149, 0x2000, v156
	v_or_b32_e32 v148, 0x2800, v156
	v_or_b32_e32 v147, 0x3000, v156
	v_or_b32_e32 v146, 0x3800, v156
	v_lshl_add_u64 v[138:139], s[0:1], 0, v[178:179]
	v_lshl_add_u64 v[140:141], s[0:1], 0, v[180:181]
	v_lshl_add_u64 v[142:143], s[0:1], 0, v[194:195]
	v_lshl_add_u64 v[144:145], s[0:1], 0, v[196:197]
	s_mov_b64 s[0:1], 0
	s_mov_b32 s38, 0
	v_add_u32_e32 v244, 0x10000, v185
	s_nop 0
	v_readfirstlane_b32 s54, v244
	s_mov_b32 m0, s54
	v_lshl_add_u64 v[208:209], v[130:131], 0, s[0:1]
	global_load_lds_dwordx4 v[208:209], off
	s_add_u32 m0, s54, 0x8000
	v_lshl_add_u64 v[208:209], v[138:139], 0, s[0:1]
	global_load_lds_dwordx4 v[208:209], off
	s_add_u32 m0, s54, 0x2000
	v_lshl_add_u64 v[208:209], v[132:133], 0, s[0:1]
	global_load_lds_dwordx4 v[208:209], off
	s_add_u32 m0, s54, 0xa000
	v_lshl_add_u64 v[208:209], v[140:141], 0, s[0:1]
	global_load_lds_dwordx4 v[208:209], off
	s_add_u32 m0, s54, 0x4000
	v_lshl_add_u64 v[208:209], v[134:135], 0, s[0:1]
	global_load_lds_dwordx4 v[208:209], off
	s_add_u32 m0, s54, 0xc000
	v_lshl_add_u64 v[208:209], v[142:143], 0, s[0:1]
	global_load_lds_dwordx4 v[208:209], off
	s_add_u32 m0, s54, 0x6000
	v_lshl_add_u64 v[208:209], v[136:137], 0, s[0:1]
	global_load_lds_dwordx4 v[208:209], off
	s_add_u32 m0, s54, 0xe000
	v_lshl_add_u64 v[208:209], v[144:145], 0, s[0:1]
	global_load_lds_dwordx4 v[208:209], off
	v_mov_b32_e32 v3, v2
	v_mov_b32_e32 v4, v2
	v_mov_b32_e32 v5, v2
	v_mov_b32_e32 v6, v2
	v_mov_b32_e32 v7, v2
	v_mov_b32_e32 v8, v2
	v_mov_b32_e32 v9, v2
	v_mov_b32_e32 v10, v2
	v_mov_b32_e32 v11, v2
	v_mov_b32_e32 v12, v2
	v_mov_b32_e32 v13, v2
	v_mov_b32_e32 v14, v2
	v_mov_b32_e32 v15, v2
	v_mov_b32_e32 v16, v2
	v_mov_b32_e32 v17, v2
	v_mov_b32_e32 v18, v2
	v_mov_b32_e32 v19, v2
	v_mov_b32_e32 v20, v2
	v_mov_b32_e32 v21, v2
	v_mov_b32_e32 v22, v2
	v_mov_b32_e32 v23, v2
	v_mov_b32_e32 v24, v2
	v_mov_b32_e32 v25, v2
	v_mov_b32_e32 v26, v2
	v_mov_b32_e32 v27, v2
	v_mov_b32_e32 v28, v2
	v_mov_b32_e32 v29, v2
	v_mov_b32_e32 v30, v2
	v_mov_b32_e32 v31, v2
	v_mov_b32_e32 v32, v2
	v_mov_b32_e32 v33, v2
	v_mov_b32_e32 v34, v2
	v_mov_b32_e32 v35, v2
	v_mov_b32_e32 v36, v2
	v_mov_b32_e32 v37, v2
	v_mov_b32_e32 v38, v2
	v_mov_b32_e32 v39, v2
	v_mov_b32_e32 v40, v2
	v_mov_b32_e32 v41, v2
	v_mov_b32_e32 v42, v2
	v_mov_b32_e32 v43, v2
	v_mov_b32_e32 v44, v2
	v_mov_b32_e32 v45, v2
	v_mov_b32_e32 v46, v2
	v_mov_b32_e32 v47, v2
	v_mov_b32_e32 v48, v2
	v_mov_b32_e32 v49, v2
	v_mov_b32_e32 v50, v2
	v_mov_b32_e32 v51, v2
	v_mov_b32_e32 v52, v2
	v_mov_b32_e32 v53, v2
	v_mov_b32_e32 v54, v2
	v_mov_b32_e32 v55, v2
	v_mov_b32_e32 v56, v2
	v_mov_b32_e32 v57, v2
	v_mov_b32_e32 v58, v2
	v_mov_b32_e32 v59, v2
	v_mov_b32_e32 v60, v2
	v_mov_b32_e32 v61, v2
	v_mov_b32_e32 v62, v2
	v_mov_b32_e32 v63, v2
	v_mov_b32_e32 v64, v2
	v_mov_b32_e32 v65, v2
	v_mov_b32_e32 v66, v2
	v_mov_b32_e32 v67, v2
	v_mov_b32_e32 v68, v2
	v_mov_b32_e32 v69, v2
	v_mov_b32_e32 v70, v2
	v_mov_b32_e32 v71, v2
	v_mov_b32_e32 v72, v2
	v_mov_b32_e32 v73, v2
	v_mov_b32_e32 v74, v2
	v_mov_b32_e32 v75, v2
	v_mov_b32_e32 v76, v2
	v_mov_b32_e32 v77, v2
	v_mov_b32_e32 v78, v2
	v_mov_b32_e32 v79, v2
	v_mov_b32_e32 v80, v2
	v_mov_b32_e32 v81, v2
	v_mov_b32_e32 v82, v2
	v_mov_b32_e32 v83, v2
	v_mov_b32_e32 v84, v2
	v_mov_b32_e32 v85, v2
	v_mov_b32_e32 v86, v2
	v_mov_b32_e32 v87, v2
	v_mov_b32_e32 v88, v2
	v_mov_b32_e32 v89, v2
	v_mov_b32_e32 v90, v2
	v_mov_b32_e32 v91, v2
	v_mov_b32_e32 v92, v2
	v_mov_b32_e32 v93, v2
	v_mov_b32_e32 v94, v2
	v_mov_b32_e32 v95, v2
	v_mov_b32_e32 v96, v2
	v_mov_b32_e32 v97, v2
	v_mov_b32_e32 v98, v2
	v_mov_b32_e32 v99, v2
	v_mov_b32_e32 v100, v2
	v_mov_b32_e32 v101, v2
	v_mov_b32_e32 v102, v2
	v_mov_b32_e32 v103, v2
	v_mov_b32_e32 v104, v2
	v_mov_b32_e32 v105, v2
	v_mov_b32_e32 v106, v2
	v_mov_b32_e32 v107, v2
	v_mov_b32_e32 v108, v2
	v_mov_b32_e32 v109, v2
	v_mov_b32_e32 v110, v2
	v_mov_b32_e32 v111, v2
	v_mov_b32_e32 v112, v2
	v_mov_b32_e32 v113, v2
	v_mov_b32_e32 v114, v2
	v_mov_b32_e32 v115, v2
	v_mov_b32_e32 v116, v2
	v_mov_b32_e32 v117, v2
	v_mov_b32_e32 v118, v2
	v_mov_b32_e32 v119, v2
	v_mov_b32_e32 v120, v2
	v_mov_b32_e32 v121, v2
	v_mov_b32_e32 v122, v2
	v_mov_b32_e32 v123, v2
	v_mov_b32_e32 v124, v2
	v_mov_b32_e32 v125, v2
	v_mov_b32_e32 v126, v2
	v_mov_b32_e32 v127, v2
	v_mov_b32_e32 v128, v2
	v_mov_b32_e32 v129, v2
	s_mov_b32 s54, 0
	v_add3_u32 v0, s54, v155, v153
	v_add3_u32 v157, s54, v155, v156
	v_add3_u32 v238, s54, v154, v152
	v_add3_u32 v240, s54, v154, v149
	v_add3_u32 v242, s54, v154, v147
	v_add3_u32 v207, s54, v154, v150
	v_add3_u32 v239, s54, v154, v151
	v_add3_u32 v241, s54, v154, v148
	v_add3_u32 v243, s54, v154, v146
	ds_read_b128 v[158:161], v0 offset:32768
	ds_read_b128 v[162:165], v0 offset:34816
	ds_read_b128 v[174:177], v157
	ds_read_b128 v[186:189], v207
	ds_read_b128 v[190:193], v238
	ds_read_b128 v[212:215], v239
	ds_read_b128 v[222:225], v240
	ds_read_b128 v[226:229], v241
	ds_read_b128 v[230:233], v242
	ds_read_b128 v[234:237], v243
	ds_read_b128 v[166:169], v0 offset:36864
	ds_read_b128 v[170:173], v0 offset:38912

; DI void g8_decode(int u, int x, int nN, int& pm, int& pn) {
;   const int ng = u >> 6, rem = u & 63;
;   int gn = nN - 4 * ng; if (gn > 4) gn = 4;
;   const int mg = rem / (8 * gn), jj = rem % (8 * gn);
;   pm = 16 * x + 8 * mg + (jj & 7); pn = 4 * ng + (jj >> 3);
; }
; template <class Epi>
; DI void gemm8_phase(int x, int j, const bf16_t* __restrict__ A, int lda, const bf16_t* __restrict__ Bt, int K, int N, int a_grp, const Epi epi) {
;     ...
;   for (int u = j; u < total; u += nb) {
;     int pm, pn; g8_decode(u, x, nN, pm, pn);
;     const int brow = pm * 256, bcol = pn * 256;
;     const bf16_t* Ab = A + (size_t)brow * lda + (a_grp ? (bcol / a_grp) * K : 0);
;     const bf16_t* Bb = Bt + (size_t)bcol * ldb;
;     const bool has_next = (u + nb < total);
;     const bf16_t* Abn = Ab; const bf16_t* Bbn = Bb;
;     if (has_next) {
;       int pm2, pn2; g8_decode(u + nb, x, nN, pm2, pn2);
;       Abn = A + (size_t)(pm2 * 256) * lda + (a_grp ? ((pn2 * 256) / a_grp) * K : 0);
;       Bbn = Bt + (size_t)(pn2 * 256) * ldb;
;     }
.LBB0_1505:
	s_ashr_i32 s1, s71, 4
	s_and_b32 s1, s1, -4
	s_sub_i32 s6, 4, s1
	s_min_i32 s6, s6, 4
	s_lshl_b32 s7, s6, 3
	s_ashr_i32 s74, s6, 31
	s_abs_i32 s6, s7
	s_and_b32 s0, s71, 63
	s_ff1_i32_b32 s9, s6
	s_lshr_b32 s6, s0, s9
	s_xor_b32 s75, s6, s74
	s_sub_i32 s6, s75, s74
	s_mul_i32 s7, s6, s7
	s_sub_i32 s0, s0, s7
	s_lshl_b32 s6, s6, 3
	s_add_i32 s6, s6, s28
	s_and_b32 s78, s0, 7
	s_lshr_b32 s0, s0, 3
	s_or_b32 s6, s6, s78
	s_add_i32 s7, s0, s1
	s_lshl_b32 s31, s6, 8
	s_lshl_b32 s8, s7, 8
	s_mul_i32 s6, s6, 0x88000
	s_mul_hi_i32 s0, s31, 0x880
	s_add_u32 s6, s52, s6
	s_addc_u32 s10, s53, s0
	s_ashr_i32 s9, s8, 31
	s_lshl_b64 s[0:1], s[8:9], 1
	s_add_u32 s14, s6, s0
	s_addc_u32 s15, s10, s1
	s_mul_i32 s9, s7, 0x28000
	s_mul_hi_i32 s79, s8, 0x280
	s_add_u32 s56, s2, s9
	s_addc_u32 s57, s3, s79
	s_add_i32 s71, s71, s33
	s_cmp_lt_i32 s71, 64
	s_cselect_b64 s[38:39], -1, 0
	s_cmp_gt_i32 s71, 63
	s_cselect_b64 s[6:7], -1, 0
	s_and_b64 vcc, exec, s[6:7]
	s_mov_b64 s[10:11], s[14:15]
	s_mov_b64 s[12:13], s[56:57]
	s_cbranch_vccnz .LBB0_1507
	s_ashr_i32 s10, s71, 4
	s_and_b32 s10, s10, -4
	s_sub_i32 s11, 4, s10
	s_min_i32 s11, s11, 4
	s_lshl_b32 s12, s11, 3
	s_abs_i32 s13, s12
	s_and_b32 s81, s71, 63
	s_ashr_i32 s11, s11, 31
	s_ff1_i32_b32 s85, s13
	s_lshr_b32 s13, s81, s85
	s_xor_b32 s13, s13, s11
	s_sub_i32 s11, s13, s11
	s_mul_i32 s12, s11, s12
	s_lshl_b32 s11, s11, 3
	s_sub_i32 s12, s81, s12
	s_add_i32 s11, s11, s28
	s_and_b32 s13, s12, 7
	s_lshr_b32 s12, s12, 3
	s_or_b32 s11, s11, s13
	s_add_i32 s81, s12, s10
	s_lshl_b32 s10, s11, 8
	s_mul_i32 s11, s11, 0x88000
	s_mul_hi_i32 s10, s10, 0x880
	s_add_u32 s84, s52, s11
	s_addc_u32 s85, s53, s10
	s_lshl_b32 s12, s81, 8
	s_ashr_i32 s13, s12, 31
	s_lshl_b64 s[10:11], s[12:13], 1
	s_add_u32 s10, s84, s10
	s_addc_u32 s11, s85, s11
	s_mul_i32 s81, s81, 0x28000
	s_mul_hi_i32 s13, s12, 0x280
	s_add_u32 s12, s2, s81
	s_addc_u32 s13, s3, s13

; DI int opaque_tid512() { int t = threadIdx.x; asm volatile("" : "+v"(t)); return t; }
; #define G8_STAGE(buf_, ap_, bp_) G8_STAGE_R(buf_, ap_, bp_, 0, 4)
; template <class Epi>
; DI void gemm8_tile(const bf16_t* __restrict__ Ab, int lda, const bf16_t* __restrict__ Bb, int ldb, int K, int brow, int bcol, const Epi epi,
;                    bool staged, bool has_next, const bf16_t* __restrict__ Abn, const bf16_t* __restrict__ Bbn) {
;   const int tid = opaque_tid512(), wid = tid >> 6, lane = tid & 63, wr = wid >> 2, wc = wid & 3, fr = lane & 15, fq = lane >> 4;
;   unsigned aoff[4], boff[4];
; #pragma unroll
;   for (int i = 0; i < 4; ++i) { int R, C; stage_rc2(wid * 1024 + i * 8192 + lane * 16, R, C); aoff[i] = (unsigned)R * (unsigned)lda + (unsigned)C; boff[i] = (unsigned)R * (unsigned)ldb + (unsigned)C; }
;     ...
;   f32x4 acc[8][4];
; #pragma unroll
;   for (int m = 0; m < 8; ++m)
; #pragma unroll
;     for (int n = 0; n < 4; ++n) acc[m][n] = (f32x4){0.f, 0.f, 0.f, 0.f};
;   const int nt = K / 64;
;   if (!staged) {
;     G8_STAGE(0, Ab, Bb);
;     asm volatile("s_waitcnt vmcnt(0)" ::: "memory");
;     __syncthreads();
;   }
;   for (int t = 0; t < nt; ++t) {
;     const int cur = t & 1;
;     const unsigned char* sa = smem + cur * G8_STAGE_B;
;     const unsigned char* sb = sa + G8_TILE_B;
; #pragma unroll
;     for (int ks = 0; ks < 2; ++ks) {
;       bf16x8 At[8], Bf[4];
;       Bf[0] = *(const bf16x8*)(sb + lds_byte2(wc * 64 + fr, ks * 32 + fq * 8));
;       At[0] = *(const bf16x8*)(sa + lds_byte2(wr * 128 + fr, ks * 32 + fq * 8));
; #pragma unroll
;       for (int n = 1; n < 4; ++n) Bf[n] = *(const bf16x8*)(sb + lds_byte2(wc * 64 + n * 16 + fr, ks * 32 + fq * 8));
; #pragma unroll
;       for (int m = 1; m < 8; ++m) At[m] = *(const bf16x8*)(sa + lds_byte2(wr * 128 + m * 16 + fr, ks * 32 + fq * 8));
;       {
;         __builtin_amdgcn_sched_barrier(0);
;         if (t + 1 < nt) { G8_STAGE_R(cur ^ 1, Ab + (t + 1) * 64, Bb + (t + 1) * 64, 2 * ks, 2 * ks + 2); }
;         else if (has_next) { G8_STAGE_R(0, Abn, Bbn, 2 * ks, 2 * ks + 2); }
.LBB0_1509:
	s_lshl_b32 s14, s75, 3
	s_add_i32 s14, s28, s14
	s_add_i32 s14, s14, s78
	s_lshl_b32 s15, s74, 3
	s_sub_i32 s14, s14, s15
	s_lshl_b32 s15, s14, 8
	s_add_u32 s0, s91, s0
	s_mul_i32 s14, s14, 0x88000
	s_addc_u32 s1, s72, s1
	v_and_b32_e32 v200, 15, v2
	s_mul_hi_i32 s15, s15, 0x880
	s_add_u32 s0, s0, s14
	v_and_b32_e32 v208, 63, v2
	v_ashrrev_i32_e32 v4, 8, v2
	v_and_b32_e32 v206, 3, v3
	v_and_b32_e32 v3, 48, v2
	v_lshlrev_b32_e32 v201, 2, v200
	v_lshlrev_b32_e32 v2, 6, v2
	s_addc_u32 s1, s1, s15
	v_and_b32_e32 v6, 32, v201
	v_and_b32_e32 v2, 0x3c0, v2
	v_lshl_add_u64 v[130:131], v[178:179], 1, s[0:1]
	v_lshl_add_u64 v[132:133], v[182:183], 1, s[0:1]
	v_lshl_add_u64 v[134:135], v[194:195], 1, s[0:1]
	v_lshl_add_u64 v[136:137], v[198:199], 1, s[0:1]
	s_add_u32 s0, s59, s9
	v_lshlrev_b32_e32 v5, 6, v200
	v_lshlrev_b32_e32 v156, 14, v4
	v_bitop3_b32 v154, v2, v6, v3 bitop3:0x36
	s_addc_u32 s1, s70, s79
	v_mov_b32_e32 v2, 0
	v_lshlrev_b32_e32 v153, 13, v206
	v_bitop3_b32 v155, v5, v6, v3 bitop3:0x36
	v_lshlrev_b32_e32 v207, 7, v4
	v_or_b32_e32 v150, 0x800, v156
	v_or_b32_e32 v152, 0x1000, v156
	v_or_b32_e32 v151, 0x1800, v156
	v_or_b32_e32 v149, 0x2000, v156
	v_or_b32_e32 v148, 0x2800, v156
	v_or_b32_e32 v147, 0x3000, v156
	v_or_b32_e32 v146, 0x3800, v156
	v_lshl_add_u64 v[138:139], v[180:181], 1, s[0:1]
	v_lshl_add_u64 v[140:141], v[184:185], 1, s[0:1]
	v_lshl_add_u64 v[142:143], v[196:197], 1, s[0:1]
	v_lshl_add_u64 v[144:145], v[0:1], 1, s[0:1]
	s_mov_b64 s[0:1], 0
	s_mov_b32 s9, 0
	v_add_u32_e32 v251, 0x10000, v189
	s_nop 0
	v_readfirstlane_b32 s15, v251
	s_mov_b32 m0, s15
	v_lshl_add_u64 v[242:243], v[130:131], 0, s[0:1]
	global_load_lds_dwordx4 v[242:243], off
	s_add_u32 m0, s15, 0x8000
	v_lshl_add_u64 v[242:243], v[138:139], 0, s[0:1]
	global_load_lds_dwordx4 v[242:243], off
	s_add_u32 m0, s15, 0x2000
	v_lshl_add_u64 v[242:243], v[132:133], 0, s[0:1]
	global_load_lds_dwordx4 v[242:243], off
	s_add_u32 m0, s15, 0xa000
	v_lshl_add_u64 v[242:243], v[140:141], 0, s[0:1]
	global_load_lds_dwordx4 v[242:243], off
	s_add_u32 m0, s15, 0x4000
	v_lshl_add_u64 v[242:243], v[134:135], 0, s[0:1]
	global_load_lds_dwordx4 v[242:243], off
	s_add_u32 m0, s15, 0xc000
	v_lshl_add_u64 v[242:243], v[142:143], 0, s[0:1]
	global_load_lds_dwordx4 v[242:243], off
	s_add_u32 m0, s15, 0x6000
	v_lshl_add_u64 v[242:243], v[136:137], 0, s[0:1]
	global_load_lds_dwordx4 v[242:243], off
	s_add_u32 m0, s15, 0xe000
	v_lshl_add_u64 v[242:243], v[144:145], 0, s[0:1]
	global_load_lds_dwordx4 v[242:243], off
	v_mov_b32_e32 v3, v2
	v_mov_b32_e32 v4, v2
	v_mov_b32_e32 v5, v2
	v_mov_b32_e32 v6, v2
	v_mov_b32_e32 v7, v2
	v_mov_b32_e32 v8, v2
	v_mov_b32_e32 v9, v2
	v_mov_b32_e32 v10, v2
	v_mov_b32_e32 v11, v2
	v_mov_b32_e32 v12, v2
	v_mov_b32_e32 v13, v2
	v_mov_b32_e32 v14, v2
	v_mov_b32_e32 v15, v2
	v_mov_b32_e32 v16, v2
	v_mov_b32_e32 v17, v2
	v_mov_b32_e32 v18, v2
	v_mov_b32_e32 v19, v2
	v_mov_b32_e32 v20, v2
	v_mov_b32_e32 v21, v2
	v_mov_b32_e32 v22, v2
	v_mov_b32_e32 v23, v2
	v_mov_b32_e32 v24, v2
	v_mov_b32_e32 v25, v2
	v_mov_b32_e32 v26, v2
	v_mov_b32_e32 v27, v2
	v_mov_b32_e32 v28, v2
	v_mov_b32_e32 v29, v2
	v_mov_b32_e32 v30, v2
	v_mov_b32_e32 v31, v2
	v_mov_b32_e32 v32, v2
	v_mov_b32_e32 v33, v2
	v_mov_b32_e32 v34, v2
	v_mov_b32_e32 v35, v2
	v_mov_b32_e32 v36, v2
	v_mov_b32_e32 v37, v2
	v_mov_b32_e32 v38, v2
	v_mov_b32_e32 v39, v2
	v_mov_b32_e32 v40, v2
	v_mov_b32_e32 v41, v2
	v_mov_b32_e32 v42, v2
	v_mov_b32_e32 v43, v2
	v_mov_b32_e32 v44, v2
	v_mov_b32_e32 v45, v2
	v_mov_b32_e32 v46, v2
	v_mov_b32_e32 v47, v2
	v_mov_b32_e32 v48, v2
	v_mov_b32_e32 v49, v2
	v_mov_b32_e32 v50, v2
	v_mov_b32_e32 v51, v2
	v_mov_b32_e32 v52, v2
	v_mov_b32_e32 v53, v2
	v_mov_b32_e32 v54, v2
	v_mov_b32_e32 v55, v2
	v_mov_b32_e32 v56, v2
	v_mov_b32_e32 v57, v2
	v_mov_b32_e32 v58, v2
	v_mov_b32_e32 v59, v2
	v_mov_b32_e32 v60, v2
	v_mov_b32_e32 v61, v2
	v_mov_b32_e32 v62, v2
	v_mov_b32_e32 v63, v2
	v_mov_b32_e32 v64, v2
	v_mov_b32_e32 v65, v2
	v_mov_b32_e32 v66, v2
	v_mov_b32_e32 v67, v2
	v_mov_b32_e32 v68, v2
	v_mov_b32_e32 v69, v2
	v_mov_b32_e32 v70, v2
	v_mov_b32_e32 v71, v2
	v_mov_b32_e32 v72, v2
	v_mov_b32_e32 v73, v2
	v_mov_b32_e32 v74, v2
	v_mov_b32_e32 v75, v2
	v_mov_b32_e32 v76, v2
	v_mov_b32_e32 v77, v2
	v_mov_b32_e32 v78, v2
	v_mov_b32_e32 v79, v2
	v_mov_b32_e32 v80, v2
	v_mov_b32_e32 v81, v2
	v_mov_b32_e32 v82, v2
	v_mov_b32_e32 v83, v2
	v_mov_b32_e32 v84, v2
	v_mov_b32_e32 v85, v2
	v_mov_b32_e32 v86, v2
	v_mov_b32_e32 v87, v2
	v_mov_b32_e32 v88, v2
	v_mov_b32_e32 v89, v2
	v_mov_b32_e32 v90, v2
	v_mov_b32_e32 v91, v2
	v_mov_b32_e32 v92, v2
	v_mov_b32_e32 v93, v2
	v_mov_b32_e32 v94, v2
	v_mov_b32_e32 v95, v2
	v_mov_b32_e32 v96, v2
	v_mov_b32_e32 v97, v2
	v_mov_b32_e32 v98, v2
	v_mov_b32_e32 v99, v2
	v_mov_b32_e32 v100, v2
	v_mov_b32_e32 v101, v2
	v_mov_b32_e32 v102, v2
	v_mov_b32_e32 v103, v2
	v_mov_b32_e32 v104, v2
	v_mov_b32_e32 v105, v2
	v_mov_b32_e32 v106, v2
	v_mov_b32_e32 v107, v2
	v_mov_b32_e32 v108, v2
	v_mov_b32_e32 v109, v2
	v_mov_b32_e32 v110, v2
	v_mov_b32_e32 v111, v2
	v_mov_b32_e32 v112, v2
	v_mov_b32_e32 v113, v2
	v_mov_b32_e32 v114, v2
	v_mov_b32_e32 v115, v2
	v_mov_b32_e32 v116, v2
	v_mov_b32_e32 v117, v2
	v_mov_b32_e32 v118, v2
	v_mov_b32_e32 v119, v2
	v_mov_b32_e32 v120, v2
	v_mov_b32_e32 v121, v2
	v_mov_b32_e32 v122, v2
	v_mov_b32_e32 v123, v2
	v_mov_b32_e32 v124, v2
	v_mov_b32_e32 v125, v2
	v_mov_b32_e32 v126, v2
	v_mov_b32_e32 v127, v2
	v_mov_b32_e32 v128, v2
	v_mov_b32_e32 v129, v2
	s_mov_b32 s15, 0
	v_add3_u32 v157, s15, v155, v153
	v_add3_u32 v209, s15, v155, v156
	v_add3_u32 v245, s15, v154, v152
	v_add3_u32 v247, s15, v154, v149
	v_add3_u32 v249, s15, v154, v147
	v_add3_u32 v244, s15, v154, v150
	v_add3_u32 v246, s15, v154, v151
	v_add3_u32 v248, s15, v154, v148
	v_add3_u32 v250, s15, v154, v146
	ds_read_b128 v[158:161], v157 offset:32768
	ds_read_b128 v[162:165], v157 offset:34816
	ds_read_b128 v[174:177], v209
	ds_read_b128 v[190:193], v244
	ds_read_b128 v[212:215], v245
	ds_read_b128 v[222:225], v246
	ds_read_b128 v[226:229], v247
	ds_read_b128 v[230:233], v248
	ds_read_b128 v[234:237], v249
	ds_read_b128 v[238:241], v250
	ds_read_b128 v[166:169], v157 offset:36864
	ds_read_b128 v[170:173], v157 offset:38912

; DI void g8_decode(int u, int x, int nN, int& pm, int& pn) {
;   const int ng = u >> 6, rem = u & 63;
;   int gn = nN - 4 * ng; if (gn > 4) gn = 4;
;   const int mg = rem / (8 * gn), jj = rem % (8 * gn);
;   pm = 16 * x + 8 * mg + (jj & 7); pn = 4 * ng + (jj >> 3);
; }
; template <class Epi>
; DI void gemm8_phase(int x, int j, const bf16_t* __restrict__ A, int lda, const bf16_t* __restrict__ Bt, int K, int N, int a_grp, const Epi epi) {
;     ...
;   for (int u = j; u < total; u += nb) {
;     int pm, pn; g8_decode(u, x, nN, pm, pn);
;     const int brow = pm * 256, bcol = pn * 256;
;     const bf16_t* Ab = A + (size_t)brow * lda + (a_grp ? (bcol / a_grp) * K : 0);
;     const bf16_t* Bb = Bt + (size_t)bcol * ldb;
;     const bool has_next = (u + nb < total);
;     const bf16_t* Abn = Ab; const bf16_t* Bbn = Bb;
;     if (has_next) {
;       int pm2, pn2; g8_decode(u + nb, x, nN, pm2, pn2);
;       Abn = A + (size_t)(pm2 * 256) * lda + (a_grp ? ((pn2 * 256) / a_grp) * K : 0);
;       Bbn = Bt + (size_t)(pn2 * 256) * ldb;
;     }
.LBB0_1668:
	s_ashr_i32 s6, s2, 4
	s_and_b32 s6, s6, -4
	s_sub_i32 s7, 22, s6
	s_min_i32 s7, s7, 4
	s_lshl_b32 s8, s7, 3
	s_ashr_i32 s54, s7, 31
	s_abs_i32 s7, s8
	s_and_b32 s3, s2, 63
	s_ff1_i32_b32 s10, s7
	s_lshr_b32 s7, s3, s10
	s_xor_b32 s55, s7, s54
	s_sub_i32 s7, s55, s54
	s_mul_i32 s8, s7, s8
	s_sub_i32 s3, s3, s8
	s_lshl_b32 s7, s7, 3
	s_add_i32 s7, s7, s28
	s_and_b32 s56, s3, 7
	s_lshr_b32 s3, s3, 3
	s_or_b32 s7, s7, s56
	s_add_i32 s6, s3, s6
	s_lshl_b32 s3, s7, 8
	s_lshl_b32 s31, s6, 8
	s_mul_i32 s7, s7, 0x88000
	s_mul_hi_i32 s8, s3, 0x880
	s_add_u32 s14, s50, s7
	s_addc_u32 s15, s51, s8
	s_mul_i32 s57, s6, 0x88000
	s_mul_hi_i32 s58, s31, 0x880
	s_add_u32 s38, s20, s57
	s_addc_u32 s39, s21, s58
	s_add_i32 s2, s2, s33
	s_cmpk_lt_i32 s2, 0x160
	s_cselect_b64 s[12:13], -1, 0
	s_cmpk_gt_i32 s2, 0x15f
	s_cselect_b64 s[6:7], -1, 0
	s_and_b64 vcc, exec, s[6:7]
	s_mov_b64 s[8:9], s[14:15]
	s_mov_b64 s[10:11], s[38:39]
	s_cbranch_vccnz .LBB0_1670
	s_ashr_i32 s8, s2, 4
	s_and_b32 s8, s8, -4
	s_sub_i32 s9, 22, s8
	s_min_i32 s9, s9, 4
	s_lshl_b32 s10, s9, 3
	s_abs_i32 s11, s10
	s_and_b32 s59, s2, 63
	s_ashr_i32 s9, s9, 31
	s_ff1_i32_b32 s71, s11
	s_lshr_b32 s11, s59, s71
	s_xor_b32 s11, s11, s9
	s_sub_i32 s9, s11, s9
	s_mul_i32 s10, s9, s10
	s_lshl_b32 s9, s9, 3
	s_sub_i32 s10, s59, s10
	s_add_i32 s9, s9, s28
	s_and_b32 s11, s10, 7
	s_lshr_b32 s10, s10, 3
	s_or_b32 s9, s9, s11
	s_add_i32 s10, s10, s8
	s_lshl_b32 s8, s9, 8
	s_mul_i32 s9, s9, 0x88000
	s_mul_hi_i32 s11, s8, 0x880
	s_add_u32 s8, s50, s9
	s_addc_u32 s9, s51, s11
	s_lshl_b32 s11, s10, 8
	s_mul_i32 s10, s10, 0x88000
	s_mul_hi_i32 s11, s11, 0x880
	s_add_u32 s10, s20, s10
	s_addc_u32 s11, s21, s11

; DI int opaque_tid512() { int t = threadIdx.x; asm volatile("" : "+v"(t)); return t; }
; #define G8_STAGE(buf_, ap_, bp_) G8_STAGE_R(buf_, ap_, bp_, 0, 4)
; template <class Epi>
; DI void gemm8_tile(const bf16_t* __restrict__ Ab, int lda, const bf16_t* __restrict__ Bb, int ldb, int K, int brow, int bcol, const Epi epi,
;                    bool staged, bool has_next, const bf16_t* __restrict__ Abn, const bf16_t* __restrict__ Bbn) {
;   const int tid = opaque_tid512(), wid = tid >> 6, lane = tid & 63, wr = wid >> 2, wc = wid & 3, fr = lane & 15, fq = lane >> 4;
;   unsigned aoff[4], boff[4];
; #pragma unroll
;   for (int i = 0; i < 4; ++i) { int R, C; stage_rc2(wid * 1024 + i * 8192 + lane * 16, R, C); aoff[i] = (unsigned)R * (unsigned)lda + (unsigned)C; boff[i] = (unsigned)R * (unsigned)ldb + (unsigned)C; }
;     ...
;   f32x4 acc[8][4];
; #pragma unroll
;   for (int m = 0; m < 8; ++m)
; #pragma unroll
;     for (int n = 0; n < 4; ++n) acc[m][n] = (f32x4){0.f, 0.f, 0.f, 0.f};
;   const int nt = K / 64;
;   if (!staged) {
;     G8_STAGE(0, Ab, Bb);
;     asm volatile("s_waitcnt vmcnt(0)" ::: "memory");
;     __syncthreads();
;   }
;   for (int t = 0; t < nt; ++t) {
;     const int cur = t & 1;
;     const unsigned char* sa = smem + cur * G8_STAGE_B;
;     const unsigned char* sb = sa + G8_TILE_B;
; #pragma unroll
;     for (int ks = 0; ks < 2; ++ks) {
;       bf16x8 At[8], Bf[4];
;       Bf[0] = *(const bf16x8*)(sb + lds_byte2(wc * 64 + fr, ks * 32 + fq * 8));
;       At[0] = *(const bf16x8*)(sa + lds_byte2(wr * 128 + fr, ks * 32 + fq * 8));
; #pragma unroll
;       for (int n = 1; n < 4; ++n) Bf[n] = *(const bf16x8*)(sb + lds_byte2(wc * 64 + n * 16 + fr, ks * 32 + fq * 8));
; #pragma unroll
;       for (int m = 1; m < 8; ++m) At[m] = *(const bf16x8*)(sa + lds_byte2(wr * 128 + m * 16 + fr, ks * 32 + fq * 8));
;       {
;         __builtin_amdgcn_sched_barrier(0);
;         if (t + 1 < nt) { G8_STAGE_R(cur ^ 1, Ab + (t + 1) * 64, Bb + (t + 1) * 64, 2 * ks, 2 * ks + 2); }
;         else if (has_next) { G8_STAGE_R(0, Abn, Bbn, 2 * ks, 2 * ks + 2); }
.LBB0_1672:
	v_readlane_b32 s0, v253, 23
	s_add_u32 s0, s0, s57
	v_readlane_b32 s1, v253, 24
	v_lshlrev_b64 v[212:213], 1, v[0:1]
	s_addc_u32 s1, s1, s58
	v_lshlrev_b64 v[214:215], 1, v[6:7]
	v_lshlrev_b64 v[146:147], 1, v[4:5]
	v_lshlrev_b64 v[148:149], 1, v[2:3]
	v_lshl_add_u64 v[130:131], s[0:1], 0, v[212:213]
	v_lshl_add_u64 v[132:133], s[0:1], 0, v[214:215]
	v_lshl_add_u64 v[134:135], s[0:1], 0, v[146:147]
	v_lshl_add_u64 v[136:137], s[0:1], 0, v[148:149]
	s_lshl_b32 s0, s55, 3
	s_add_i32 s0, s28, s0
	s_add_i32 s0, s0, s56
	s_lshl_b32 s1, s54, 3
	s_sub_i32 s0, s0, s1
	s_lshl_b32 s1, s0, 8
	s_mul_i32 s0, s0, 0x88000
	v_readlane_b32 s4, v253, 6
	v_and_b32_e32 v228, 63, v8
	v_and_b32_e32 v229, 3, v9
	v_ashrrev_i32_e32 v9, 8, v8
	v_and_b32_e32 v223, 15, v8
	v_and_b32_e32 v10, 48, v8
	v_lshlrev_b32_e32 v12, 2, v8
	v_lshlrev_b32_e32 v8, 6, v8
	s_mul_hi_i32 s1, s1, 0x880
	s_add_u32 s0, s4, s0
	v_readlane_b32 s4, v253, 7
	v_lshlrev_b32_e32 v11, 6, v223
	v_and_b32_e32 v12, 32, v12
	v_lshlrev_b32_e32 v158, 14, v9
	v_and_b32_e32 v8, 0x3c0, v8
	s_addc_u32 s1, s4, s1
	v_mov_b32_e32 v2, 0
	v_lshlrev_b32_e32 v151, 13, v229
	v_bitop3_b32 v153, v11, v12, v10 bitop3:0x36
	v_lshlrev_b32_e32 v230, 7, v9
	v_or_b32_e32 v150, 0x800, v158
	v_bitop3_b32 v152, v8, v12, v10 bitop3:0x36
	v_or_b32_e32 v167, 0x1000, v158
	v_or_b32_e32 v166, 0x1800, v158
	v_or_b32_e32 v165, 0x2000, v158
	v_or_b32_e32 v164, 0x2800, v158
	v_or_b32_e32 v163, 0x3000, v158
	v_or_b32_e32 v162, 0x3800, v158
	v_lshl_add_u64 v[138:139], s[0:1], 0, v[212:213]
	v_lshl_add_u64 v[140:141], s[0:1], 0, v[214:215]
	v_lshl_add_u64 v[142:143], s[0:1], 0, v[146:147]
	v_lshl_add_u64 v[144:145], s[0:1], 0, v[148:149]
	s_mov_b64 s[0:1], 0
	s_mov_b32 s14, 0
	v_add_u32_e32 v244, 0x10000, v157
	s_nop 0
	v_readfirstlane_b32 s38, v244
	s_mov_b32 m0, s38
	v_lshl_add_u64 v[160:161], v[144:145], 0, s[0:1]
	global_load_lds_dwordx4 v[160:161], off
	s_add_u32 m0, s38, 0x8000
	v_lshl_add_u64 v[160:161], v[136:137], 0, s[0:1]
	global_load_lds_dwordx4 v[160:161], off
	s_add_u32 m0, s38, 0x2000
	v_lshl_add_u64 v[160:161], v[142:143], 0, s[0:1]
	global_load_lds_dwordx4 v[160:161], off
	s_add_u32 m0, s38, 0xa000
	v_lshl_add_u64 v[160:161], v[134:135], 0, s[0:1]
	global_load_lds_dwordx4 v[160:161], off
	s_add_u32 m0, s38, 0x4000
	v_lshl_add_u64 v[160:161], v[140:141], 0, s[0:1]
	global_load_lds_dwordx4 v[160:161], off
	s_add_u32 m0, s38, 0xc000
	v_lshl_add_u64 v[160:161], v[132:133], 0, s[0:1]
	global_load_lds_dwordx4 v[160:161], off
	s_add_u32 m0, s38, 0x6000
	v_lshl_add_u64 v[160:161], v[138:139], 0, s[0:1]
	global_load_lds_dwordx4 v[160:161], off
	s_add_u32 m0, s38, 0xe000
	v_lshl_add_u64 v[160:161], v[130:131], 0, s[0:1]
	global_load_lds_dwordx4 v[160:161], off
	v_mov_b32_e32 v3, v2
	v_mov_b32_e32 v4, v2
	v_mov_b32_e32 v5, v2
	v_mov_b32_e32 v6, v2
	v_mov_b32_e32 v7, v2
	v_mov_b32_e32 v8, v2
	v_mov_b32_e32 v9, v2
	v_mov_b32_e32 v10, v2
	v_mov_b32_e32 v11, v2
	v_mov_b32_e32 v12, v2
	v_mov_b32_e32 v13, v2
	v_mov_b32_e32 v14, v2
	v_mov_b32_e32 v15, v2
	v_mov_b32_e32 v16, v2
	v_mov_b32_e32 v17, v2
	v_mov_b32_e32 v18, v2
	v_mov_b32_e32 v19, v2
	v_mov_b32_e32 v20, v2
	v_mov_b32_e32 v21, v2
	v_mov_b32_e32 v22, v2
	v_mov_b32_e32 v23, v2
	v_mov_b32_e32 v24, v2
	v_mov_b32_e32 v25, v2
	v_mov_b32_e32 v26, v2
	v_mov_b32_e32 v27, v2
	v_mov_b32_e32 v28, v2
	v_mov_b32_e32 v29, v2
	v_mov_b32_e32 v30, v2
	v_mov_b32_e32 v31, v2
	v_mov_b32_e32 v32, v2
	v_mov_b32_e32 v33, v2
	v_mov_b32_e32 v34, v2
	v_mov_b32_e32 v35, v2
	v_mov_b32_e32 v36, v2
	v_mov_b32_e32 v37, v2
	v_mov_b32_e32 v38, v2
	v_mov_b32_e32 v39, v2
	v_mov_b32_e32 v40, v2
	v_mov_b32_e32 v41, v2
	v_mov_b32_e32 v42, v2
	v_mov_b32_e32 v43, v2
	v_mov_b32_e32 v44, v2
	v_mov_b32_e32 v45, v2
	v_mov_b32_e32 v46, v2
	v_mov_b32_e32 v47, v2
	v_mov_b32_e32 v48, v2
	v_mov_b32_e32 v49, v2
	v_mov_b32_e32 v50, v2
	v_mov_b32_e32 v51, v2
	v_mov_b32_e32 v52, v2
	v_mov_b32_e32 v53, v2
	v_mov_b32_e32 v54, v2
	v_mov_b32_e32 v55, v2
	v_mov_b32_e32 v56, v2
	v_mov_b32_e32 v57, v2
	v_mov_b32_e32 v58, v2
	v_mov_b32_e32 v59, v2
	v_mov_b32_e32 v60, v2
	v_mov_b32_e32 v61, v2
	v_mov_b32_e32 v62, v2
	v_mov_b32_e32 v63, v2
	v_mov_b32_e32 v64, v2
	v_mov_b32_e32 v65, v2
	v_mov_b32_e32 v66, v2
	v_mov_b32_e32 v67, v2
	v_mov_b32_e32 v68, v2
	v_mov_b32_e32 v69, v2
	v_mov_b32_e32 v70, v2
	v_mov_b32_e32 v71, v2
	v_mov_b32_e32 v72, v2
	v_mov_b32_e32 v73, v2
	v_mov_b32_e32 v74, v2
	v_mov_b32_e32 v75, v2
	v_mov_b32_e32 v76, v2
	v_mov_b32_e32 v77, v2
	v_mov_b32_e32 v78, v2
	v_mov_b32_e32 v79, v2
	v_mov_b32_e32 v80, v2
	v_mov_b32_e32 v81, v2
	v_mov_b32_e32 v82, v2
	v_mov_b32_e32 v83, v2
	v_mov_b32_e32 v84, v2
	v_mov_b32_e32 v85, v2
	v_mov_b32_e32 v86, v2
	v_mov_b32_e32 v87, v2
	v_mov_b32_e32 v88, v2
	v_mov_b32_e32 v89, v2
	v_mov_b32_e32 v90, v2
	v_mov_b32_e32 v91, v2
	v_mov_b32_e32 v92, v2
	v_mov_b32_e32 v93, v2
	v_mov_b32_e32 v94, v2
	v_mov_b32_e32 v95, v2
	v_mov_b32_e32 v96, v2
	v_mov_b32_e32 v97, v2
	v_mov_b32_e32 v98, v2
	v_mov_b32_e32 v99, v2
	v_mov_b32_e32 v100, v2
	v_mov_b32_e32 v101, v2
	v_mov_b32_e32 v102, v2
	v_mov_b32_e32 v103, v2
	v_mov_b32_e32 v104, v2
	v_mov_b32_e32 v105, v2
	v_mov_b32_e32 v106, v2
	v_mov_b32_e32 v107, v2
	v_mov_b32_e32 v108, v2
	v_mov_b32_e32 v109, v2
	v_mov_b32_e32 v110, v2
	v_mov_b32_e32 v111, v2
	v_mov_b32_e32 v112, v2
	v_mov_b32_e32 v113, v2
	v_mov_b32_e32 v114, v2
	v_mov_b32_e32 v115, v2
	v_mov_b32_e32 v116, v2
	v_mov_b32_e32 v117, v2
	v_mov_b32_e32 v118, v2
	v_mov_b32_e32 v119, v2
	v_mov_b32_e32 v120, v2
	v_mov_b32_e32 v121, v2
	v_mov_b32_e32 v122, v2
	v_mov_b32_e32 v123, v2
	v_mov_b32_e32 v124, v2
	v_mov_b32_e32 v125, v2
	v_mov_b32_e32 v126, v2
	v_mov_b32_e32 v127, v2
	v_mov_b32_e32 v128, v2
	v_mov_b32_e32 v129, v2
	s_mov_b32 s38, 0
	v_add3_u32 v0, s38, v153, v151
	v_add3_u32 v159, s38, v153, v158
	v_add3_u32 v209, s38, v152, v167
	v_add3_u32 v240, s38, v152, v165
	v_add3_u32 v242, s38, v152, v163
	v_add3_u32 v208, s38, v152, v150
	v_add3_u32 v231, s38, v152, v166
	v_add3_u32 v241, s38, v152, v164
	v_add3_u32 v243, s38, v152, v162
	ds_read_b128 v[168:171], v0 offset:32768
	ds_read_b128 v[172:175], v0 offset:34816
	ds_read_b128 v[184:187], v159
	ds_read_b128 v[188:191], v208
	ds_read_b128 v[192:195], v209
	ds_read_b128 v[196:199], v231
	ds_read_b128 v[200:203], v240
	ds_read_b128 v[204:207], v241
	ds_read_b128 v[232:235], v242
	ds_read_b128 v[236:239], v243
	ds_read_b128 v[176:179], v0 offset:36864
	ds_read_b128 v[180:183], v0 offset:38912

; DI void g8_decode(int u, int x, int nN, int& pm, int& pn) {
;   const int ng = u >> 6, rem = u & 63;
;   int gn = nN - 4 * ng; if (gn > 4) gn = 4;
;   const int mg = rem / (8 * gn), jj = rem % (8 * gn);
;   pm = 16 * x + 8 * mg + (jj & 7); pn = 4 * ng + (jj >> 3);
; }
; template <class Epi>
; DI void gemm8_phase(int x, int j, const bf16_t* __restrict__ A, int lda, const bf16_t* __restrict__ Bt, int K, int N, int a_grp, const Epi epi) {
;     ...
;   for (int u = j; u < total; u += nb) {
;     int pm, pn; g8_decode(u, x, nN, pm, pn);
;     const int brow = pm * 256, bcol = pn * 256;
;     const bf16_t* Ab = A + (size_t)brow * lda + (a_grp ? (bcol / a_grp) * K : 0);
;     const bf16_t* Bb = Bt + (size_t)bcol * ldb;
;     const bool has_next = (u + nb < total);
;     const bf16_t* Abn = Ab; const bf16_t* Bbn = Bb;
;     if (has_next) {
;       int pm2, pn2; g8_decode(u + nb, x, nN, pm2, pn2);
;       Abn = A + (size_t)(pm2 * 256) * lda + (a_grp ? ((pn2 * 256) / a_grp) * K : 0);
;       Bbn = Bt + (size_t)(pn2 * 256) * ldb;
;     }
.LBB0_1690:
	s_ashr_i32 s4, s2, 4
	s_and_b32 s4, s4, -4
	s_sub_i32 s5, 4, s4
	s_min_i32 s5, s5, 4
	s_lshl_b32 s6, s5, 3
	s_ashr_i32 s78, s5, 31
	s_abs_i32 s5, s6
	s_and_b32 s3, s2, 63
	s_ff1_i32_b32 s14, s5
	s_lshr_b32 s5, s3, s14
	s_xor_b32 s79, s5, s78
	s_sub_i32 s5, s79, s78
	s_mul_i32 s6, s5, s6
	s_sub_i32 s3, s3, s6
	s_lshl_b32 s5, s5, 3
	s_add_i32 s5, s5, s28
	s_and_b32 s81, s3, 7
	s_lshr_b32 s3, s3, 3
	s_or_b32 s5, s5, s81
	s_add_i32 s4, s3, s4
	s_lshl_b32 s3, s5, 8
	s_lshl_b32 s31, s4, 8
	s_mul_i32 s5, s5, 0x168000
	s_mul_hi_i32 s6, s3, 0x1680
	s_add_u32 s58, s52, s5
	s_addc_u32 s59, s53, s6
	s_mul_i32 s84, s4, 0x168000
	s_mul_hi_i32 s85, s31, 0x1680
	s_add_u32 s70, s22, s84
	s_addc_u32 s71, s23, s85
	s_add_i32 s2, s2, s33
	s_cmp_lt_i32 s2, 64
	s_cselect_b64 s[14:15], -1, 0
	s_cmp_gt_i32 s2, 63
	s_cselect_b64 s[56:57], -1, 0
	s_and_b64 vcc, exec, s[56:57]
	s_mov_b64 s[4:5], s[58:59]
	s_mov_b64 s[6:7], s[70:71]
	s_cbranch_vccnz .LBB0_1692
	s_ashr_i32 s4, s2, 4
	s_and_b32 s4, s4, -4
	s_sub_i32 s5, 4, s4
	s_min_i32 s5, s5, 4
	s_lshl_b32 s6, s5, 3
	s_abs_i32 s7, s6
	s_and_b32 s87, s2, 63
	s_ashr_i32 s5, s5, 31
	s_ff1_i32_b32 s92, s7
	s_lshr_b32 s7, s87, s92
	s_xor_b32 s7, s7, s5
	s_sub_i32 s5, s7, s5
	s_mul_i32 s6, s5, s6
	s_lshl_b32 s5, s5, 3
	s_sub_i32 s6, s87, s6
	s_add_i32 s5, s5, s28
	s_and_b32 s7, s6, 7
	s_lshr_b32 s6, s6, 3
	s_or_b32 s5, s5, s7
	s_add_i32 s6, s6, s4
	s_lshl_b32 s4, s5, 8
	s_mul_i32 s5, s5, 0x168000
	s_mul_hi_i32 s7, s4, 0x1680
	s_add_u32 s4, s52, s5
	s_addc_u32 s5, s53, s7
	s_lshl_b32 s7, s6, 8
	s_mul_i32 s6, s6, 0x168000
	s_mul_hi_i32 s7, s7, 0x1680
	s_add_u32 s6, s22, s6
	s_mov_b32 s92, 0x10000
	s_addc_u32 s7, s23, s7

; DI int opaque_tid512() { int t = threadIdx.x; asm volatile("" : "+v"(t)); return t; }
; #define G8_STAGE(buf_, ap_, bp_) G8_STAGE_R(buf_, ap_, bp_, 0, 4)
; template <class Epi>
; DI void gemm8_tile(const bf16_t* __restrict__ Ab, int lda, const bf16_t* __restrict__ Bb, int ldb, int K, int brow, int bcol, const Epi epi,
;                    bool staged, bool has_next, const bf16_t* __restrict__ Abn, const bf16_t* __restrict__ Bbn) {
;   const int tid = opaque_tid512(), wid = tid >> 6, lane = tid & 63, wr = wid >> 2, wc = wid & 3, fr = lane & 15, fq = lane >> 4;
;   unsigned aoff[4], boff[4];
; #pragma unroll
;   for (int i = 0; i < 4; ++i) { int R, C; stage_rc2(wid * 1024 + i * 8192 + lane * 16, R, C); aoff[i] = (unsigned)R * (unsigned)lda + (unsigned)C; boff[i] = (unsigned)R * (unsigned)ldb + (unsigned)C; }
;     ...
;   f32x4 acc[8][4];
; #pragma unroll
;   for (int m = 0; m < 8; ++m)
; #pragma unroll
;     for (int n = 0; n < 4; ++n) acc[m][n] = (f32x4){0.f, 0.f, 0.f, 0.f};
;   const int nt = K / 64;
;   if (!staged) {
;     G8_STAGE(0, Ab, Bb);
;     asm volatile("s_waitcnt vmcnt(0)" ::: "memory");
;     __syncthreads();
;   }
;   for (int t = 0; t < nt; ++t) {
;     const int cur = t & 1;
;     const unsigned char* sa = smem + cur * G8_STAGE_B;
;     const unsigned char* sb = sa + G8_TILE_B;
; #pragma unroll
;     for (int ks = 0; ks < 2; ++ks) {
;       bf16x8 At[8], Bf[4];
;       Bf[0] = *(const bf16x8*)(sb + lds_byte2(wc * 64 + fr, ks * 32 + fq * 8));
;       At[0] = *(const bf16x8*)(sa + lds_byte2(wr * 128 + fr, ks * 32 + fq * 8));
; #pragma unroll
;       for (int n = 1; n < 4; ++n) Bf[n] = *(const bf16x8*)(sb + lds_byte2(wc * 64 + n * 16 + fr, ks * 32 + fq * 8));
; #pragma unroll
;       for (int m = 1; m < 8; ++m) At[m] = *(const bf16x8*)(sa + lds_byte2(wr * 128 + m * 16 + fr, ks * 32 + fq * 8));
;       {
;         __builtin_amdgcn_sched_barrier(0);
;         if (t + 1 < nt) { G8_STAGE_R(cur ^ 1, Ab + (t + 1) * 64, Bb + (t + 1) * 64, 2 * ks, 2 * ks + 2); }
;         else if (has_next) { G8_STAGE_R(0, Abn, Bbn, 2 * ks, 2 * ks + 2); }
.LBB0_1694:
	s_lshl_b32 s0, s79, 3
	s_add_i32 s0, s28, s0
	s_add_i32 s0, s0, s81
	s_lshl_b32 s1, s78, 3
	s_sub_i32 s0, s0, s1
	s_lshl_b32 s1, s0, 8
	s_mul_i32 s0, s0, 0x168000
	s_mul_hi_i32 s1, s1, 0x1680
	s_add_u32 s0, s91, s0
	v_lshlrev_b64 v[178:179], 1, v[4:5]
	s_addc_u32 s1, s72, s1
	v_lshlrev_b64 v[180:181], 1, v[2:3]
	v_lshlrev_b64 v[194:195], 1, v[6:7]
	v_lshlrev_b64 v[196:197], 1, v[0:1]
	v_and_b32_e32 v198, 15, v8
	v_lshl_add_u64 v[130:131], s[0:1], 0, v[178:179]
	v_lshl_add_u64 v[132:133], s[0:1], 0, v[180:181]
	v_lshl_add_u64 v[134:135], s[0:1], 0, v[194:195]
	v_lshl_add_u64 v[136:137], s[0:1], 0, v[196:197]
	v_readlane_b32 s0, v253, 25
	v_and_b32_e32 v206, 63, v8
	v_ashrrev_i32_e32 v10, 8, v8
	v_and_b32_e32 v204, 3, v9
	v_and_b32_e32 v9, 48, v8
	v_lshlrev_b32_e32 v199, 2, v198
	v_lshlrev_b32_e32 v8, 6, v8
	s_add_u32 s0, s0, s84
	v_readlane_b32 s1, v253, 26
	v_lshlrev_b32_e32 v11, 6, v198
	v_and_b32_e32 v12, 32, v199
	v_lshlrev_b32_e32 v156, 14, v10
	v_and_b32_e32 v8, 0x3c0, v8
	s_addc_u32 s1, s1, s85
	v_mov_b32_e32 v2, 0
	v_lshlrev_b32_e32 v153, 13, v204
	v_bitop3_b32 v155, v11, v12, v9 bitop3:0x36
	v_lshlrev_b32_e32 v205, 7, v10
	v_or_b32_e32 v150, 0x800, v156
	v_bitop3_b32 v154, v8, v12, v9 bitop3:0x36
	v_or_b32_e32 v152, 0x1000, v156
	v_or_b32_e32 v151, 0x1800, v156
	v_or_b32_e32 v149, 0x2000, v156
	v_or_b32_e32 v148, 0x2800, v156
	v_or_b32_e32 v147, 0x3000, v156
	v_or_b32_e32 v146, 0x3800, v156
	v_lshl_add_u64 v[138:139], s[0:1], 0, v[178:179]
	v_lshl_add_u64 v[140:141], s[0:1], 0, v[180:181]
	v_lshl_add_u64 v[142:143], s[0:1], 0, v[194:195]
	v_lshl_add_u64 v[144:145], s[0:1], 0, v[196:197]
	s_mov_b64 s[0:1], 0
	s_mov_b32 s58, 0
	v_add_u32_e32 v244, 0x10000, v185
	s_nop 0
	v_readfirstlane_b32 s70, v244
	s_mov_b32 m0, s70
	v_lshl_add_u64 v[208:209], v[130:131], 0, s[0:1]
	global_load_lds_dwordx4 v[208:209], off
	s_add_u32 m0, s70, 0x8000
	v_lshl_add_u64 v[208:209], v[138:139], 0, s[0:1]
	global_load_lds_dwordx4 v[208:209], off
	s_add_u32 m0, s70, 0x2000
	v_lshl_add_u64 v[208:209], v[132:133], 0, s[0:1]
	global_load_lds_dwordx4 v[208:209], off
	s_add_u32 m0, s70, 0xa000
	v_lshl_add_u64 v[208:209], v[140:141], 0, s[0:1]
	global_load_lds_dwordx4 v[208:209], off
	s_add_u32 m0, s70, 0x4000
	v_lshl_add_u64 v[208:209], v[134:135], 0, s[0:1]
	global_load_lds_dwordx4 v[208:209], off
	s_add_u32 m0, s70, 0xc000
	v_lshl_add_u64 v[208:209], v[142:143], 0, s[0:1]
	global_load_lds_dwordx4 v[208:209], off
	s_add_u32 m0, s70, 0x6000
	v_lshl_add_u64 v[208:209], v[136:137], 0, s[0:1]
	global_load_lds_dwordx4 v[208:209], off
	s_add_u32 m0, s70, 0xe000
	v_lshl_add_u64 v[208:209], v[144:145], 0, s[0:1]
	global_load_lds_dwordx4 v[208:209], off
	v_mov_b32_e32 v3, v2
	v_mov_b32_e32 v4, v2
	v_mov_b32_e32 v5, v2
	v_mov_b32_e32 v6, v2
	v_mov_b32_e32 v7, v2
	v_mov_b32_e32 v8, v2
	v_mov_b32_e32 v9, v2
	v_mov_b32_e32 v10, v2
	v_mov_b32_e32 v11, v2
	v_mov_b32_e32 v12, v2
	v_mov_b32_e32 v13, v2
	v_mov_b32_e32 v14, v2
	v_mov_b32_e32 v15, v2
	v_mov_b32_e32 v16, v2
	v_mov_b32_e32 v17, v2
	v_mov_b32_e32 v18, v2
	v_mov_b32_e32 v19, v2
	v_mov_b32_e32 v20, v2
	v_mov_b32_e32 v21, v2
	v_mov_b32_e32 v22, v2
	v_mov_b32_e32 v23, v2
	v_mov_b32_e32 v24, v2
	v_mov_b32_e32 v25, v2
	v_mov_b32_e32 v26, v2
	v_mov_b32_e32 v27, v2
	v_mov_b32_e32 v28, v2
	v_mov_b32_e32 v29, v2
	v_mov_b32_e32 v30, v2
	v_mov_b32_e32 v31, v2
	v_mov_b32_e32 v32, v2
	v_mov_b32_e32 v33, v2
	v_mov_b32_e32 v34, v2
	v_mov_b32_e32 v35, v2
	v_mov_b32_e32 v36, v2
	v_mov_b32_e32 v37, v2
	v_mov_b32_e32 v38, v2
	v_mov_b32_e32 v39, v2
	v_mov_b32_e32 v40, v2
	v_mov_b32_e32 v41, v2
	v_mov_b32_e32 v42, v2
	v_mov_b32_e32 v43, v2
	v_mov_b32_e32 v44, v2
	v_mov_b32_e32 v45, v2
	v_mov_b32_e32 v46, v2
	v_mov_b32_e32 v47, v2
	v_mov_b32_e32 v48, v2
	v_mov_b32_e32 v49, v2
	v_mov_b32_e32 v50, v2
	v_mov_b32_e32 v51, v2
	v_mov_b32_e32 v52, v2
	v_mov_b32_e32 v53, v2
	v_mov_b32_e32 v54, v2
	v_mov_b32_e32 v55, v2
	v_mov_b32_e32 v56, v2
	v_mov_b32_e32 v57, v2
	v_mov_b32_e32 v58, v2
	v_mov_b32_e32 v59, v2
	v_mov_b32_e32 v60, v2
	v_mov_b32_e32 v61, v2
	v_mov_b32_e32 v62, v2
	v_mov_b32_e32 v63, v2
	v_mov_b32_e32 v64, v2
	v_mov_b32_e32 v65, v2
	v_mov_b32_e32 v66, v2
	v_mov_b32_e32 v67, v2
	v_mov_b32_e32 v68, v2
	v_mov_b32_e32 v69, v2
	v_mov_b32_e32 v70, v2
	v_mov_b32_e32 v71, v2
	v_mov_b32_e32 v72, v2
	v_mov_b32_e32 v73, v2
	v_mov_b32_e32 v74, v2
	v_mov_b32_e32 v75, v2
	v_mov_b32_e32 v76, v2
	v_mov_b32_e32 v77, v2
	v_mov_b32_e32 v78, v2
	v_mov_b32_e32 v79, v2
	v_mov_b32_e32 v80, v2
	v_mov_b32_e32 v81, v2
	v_mov_b32_e32 v82, v2
	v_mov_b32_e32 v83, v2
	v_mov_b32_e32 v84, v2
	v_mov_b32_e32 v85, v2
	v_mov_b32_e32 v86, v2
	v_mov_b32_e32 v87, v2
	v_mov_b32_e32 v88, v2
	v_mov_b32_e32 v89, v2
	v_mov_b32_e32 v90, v2
	v_mov_b32_e32 v91, v2
	v_mov_b32_e32 v92, v2
	v_mov_b32_e32 v93, v2
	v_mov_b32_e32 v94, v2
	v_mov_b32_e32 v95, v2
	v_mov_b32_e32 v96, v2
	v_mov_b32_e32 v97, v2
	v_mov_b32_e32 v98, v2
	v_mov_b32_e32 v99, v2
	v_mov_b32_e32 v100, v2
	v_mov_b32_e32 v101, v2
	v_mov_b32_e32 v102, v2
	v_mov_b32_e32 v103, v2
	v_mov_b32_e32 v104, v2
	v_mov_b32_e32 v105, v2
	v_mov_b32_e32 v106, v2
	v_mov_b32_e32 v107, v2
	v_mov_b32_e32 v108, v2
	v_mov_b32_e32 v109, v2
	v_mov_b32_e32 v110, v2
	v_mov_b32_e32 v111, v2
	v_mov_b32_e32 v112, v2
	v_mov_b32_e32 v113, v2
	v_mov_b32_e32 v114, v2
	v_mov_b32_e32 v115, v2
	v_mov_b32_e32 v116, v2
	v_mov_b32_e32 v117, v2
	v_mov_b32_e32 v118, v2
	v_mov_b32_e32 v119, v2
	v_mov_b32_e32 v120, v2
	v_mov_b32_e32 v121, v2
	v_mov_b32_e32 v122, v2
	v_mov_b32_e32 v123, v2
	v_mov_b32_e32 v124, v2
	v_mov_b32_e32 v125, v2
	v_mov_b32_e32 v126, v2
	v_mov_b32_e32 v127, v2
	v_mov_b32_e32 v128, v2
	v_mov_b32_e32 v129, v2
	s_mov_b32 s70, 0
	v_add3_u32 v0, s70, v155, v153
	v_add3_u32 v157, s70, v155, v156
	v_add3_u32 v238, s70, v154, v152
	v_add3_u32 v240, s70, v154, v149
	v_add3_u32 v242, s70, v154, v147
	v_add3_u32 v207, s70, v154, v150
	v_add3_u32 v239, s70, v154, v151
	v_add3_u32 v241, s70, v154, v148
	v_add3_u32 v243, s70, v154, v146
	ds_read_b128 v[158:161], v0 offset:32768
	ds_read_b128 v[162:165], v0 offset:34816
	ds_read_b128 v[174:177], v157
	ds_read_b128 v[186:189], v207
	ds_read_b128 v[190:193], v238
	ds_read_b128 v[212:215], v239
	ds_read_b128 v[222:225], v240
	ds_read_b128 v[226:229], v241
	ds_read_b128 v[230:233], v242
	ds_read_b128 v[234:237], v243
	ds_read_b128 v[166:169], v0 offset:36864
	ds_read_b128 v[170:173], v0 offset:38912
